# speedup vs baseline: 1.0003x; 1.0003x over previous
; #define G_STAGE(bufoff, gbase, voff) do { _Pragma("unroll") for (int _i = 0; _i < 2; ++_i) \
;         __builtin_amdgcn_global_load_lds((const unsigned*)((const char*)(gbase) + (voff)[_i]), (LAS unsigned*)(lds + (bufoff) + ldsw + _i * 8192), 16, 0, 0); } while (0)
; #define G_LDA(dst, b, h) do { _Pragma("unroll") for (int m = 0; m < 4; ++m) _Pragma("unroll") for (int k = 0; k < 2; ++k) dst[m][k] = *(const LAS bf16x8*)(lds + G_SA(b, h) + aoff + m * 2048 + k * 1024); } while (0)
; #define G_LDB(dst, b, h) do { _Pragma("unroll") for (int n = 0; n < 2; ++n) _Pragma("unroll") for (int k = 0; k < 2; ++k) dst[n][k] = *(const LAS bf16x8*)(lds + G_SB(b, h) + boff + n * 2048 + k * 1024); } while (0)
; #define G_MMA(ai, bj, At, Bt) do { __builtin_amdgcn_s_setprio(1); _Pragma("unroll") for (int m = 0; m < 4; ++m) _Pragma("unroll") for (int n = 0; n < 2; ++n) _Pragma("unroll") for (int k = 0; k < 2; ++k) \
;         acc[ai][bj][m][n] = __builtin_amdgcn_mfma_f32_16x16x32_bf16(Bt[n][k], At[m][k], acc[ai][bj][m][n], 0, 0, 0); __builtin_amdgcn_s_setprio(0); } while (0)
; #define G_WAIT_L(n) asm volatile("s_waitcnt lgkmcnt(" #n ")" ::: "memory")
; #define G_BAR __builtin_amdgcn_s_barrier()
; #define G_SCHED __builtin_amdgcn_sched_barrier(0)
; template <class J>
; DI void gemm_phase(LAS unsigned char* lds, const J& job) {
;     ...
;     for (int t = 0; t < nt; t += 2) {
;       const bool last = (t == nt - 2);
;       const char* a1 = cA + G_KT(t + 1);
;       const char* a2 = last ? nA + G_KT(0) : cA + G_KT(t + 2); const char* b2 = last ? nB + G_KT(0) : cB + G_KT(t + 2);
;       const char* a3 = last ? nA + G_KT(1) : cA + G_KT(t + 3); const char* b3 = last ? nB + G_KT(1) : cB + G_KT(t + 3);
;       G_LDB(B0, 0, 0); G_SCHED; G_LDA(At, 0, 0); G_STAGE(G_SA(1, 1), a1 + hstepA, voffA);
;       G_WAIT_L(8); G_BAR; G_WAIT_L(0); G_MMA(0, 0, At, B0); G_BAR; G_SCHED;
;       G_LDB(B1, 0, 1); G_STAGE(G_SB(0, 0), b2, voffB);
;       G_BAR; G_WAIT_L(0); G_MMA(0, 1, At, B1); G_BAR;
;       G_LDA(At, 0, 1); G_STAGE(G_SA(0, 0), a2, voffA);
;       G_BAR; G_WAIT_L(0); G_MMA(1, 0, At, B0); G_BAR; G_SCHED;
.LBB0_42:
	s_add_i32 s1, s57, 0xffffff80
	s_and_b32 s0, s44, 0xf80
	s_and_b32 s1, s1, 0xf00
	s_add_u32 s2, s70, s1
	s_addc_u32 s72, s71, 0
	s_add_u32 s1, s68, s1
	s_addc_u32 s73, s69, 0
	s_and_b32 s74, s57, 0xf80
	s_add_u32 s80, s70, s74
	s_addc_u32 s75, s71, 0
	s_add_u32 s54, s68, s74
	s_addc_u32 s55, s69, 0
	s_cmp_eq_u32 s7, 28
	s_cselect_b32 s77, vcc_lo, s72
	s_cselect_b32 s76, s47, s2
	s_cselect_b32 s79, s33, s73
	s_cselect_b32 s78, vcc_hi, s1
	s_cselect_b32 s75, s4, s75
	s_cselect_b32 s74, s97, s80
	s_cselect_b32 s73, s6, s55
	s_cselect_b32 s72, s5, s54
	s_add_i32 s2, s84, 0x100
	v_add_u32_e32 v140, s2, v162
	ds_read_b128 v[128:131], v140
	ds_read_b128 v[132:135], v140 offset:1024
	ds_read_b128 v[136:139], v140 offset:2048
	ds_read_b128 v[140:143], v140 offset:3072
	s_add_u32 s0, s21, s0
	s_addc_u32 s1, s23, 0
	v_lshl_add_u64 v[158:159], s[0:1], 0, v[148:149]
	s_add_i32 m0, s25, 0xc000
	ds_read_b128 v[154:157], v163
	ds_read_b128 v[164:167], v163 offset:1024
	ds_read_b128 v[168:171], v163 offset:2048
	ds_read_b128 v[172:175], v163 offset:3072
	ds_read_b128 v[176:179], v163 offset:4096
	ds_read_b128 v[180:183], v163 offset:5120
	ds_read_b128 v[184:187], v163 offset:6144
	ds_read_b128 v[188:191], v163 offset:7168
	global_load_lds_dwordx4 v[158:159], off
	v_lshl_add_u64 v[158:159], s[0:1], 0, v[150:151]
	s_add_i32 m0, s25, 0xe000
	s_nop 0
	global_load_lds_dwordx4 v[158:159], off
	s_waitcnt lgkmcnt(8)
	s_barrier
	s_waitcnt lgkmcnt(7)
	v_mfma_f32_16x16x32_bf16 v[124:127], v[128:131], v[154:157], v[124:127]
	v_mfma_f32_16x16x32_bf16 v[120:123], v[136:139], v[154:157], v[120:123]
	s_waitcnt lgkmcnt(5)
	v_mfma_f32_16x16x32_bf16 v[108:111], v[128:131], v[168:171], v[108:111]
	v_mfma_f32_16x16x32_bf16 v[104:107], v[136:139], v[168:171], v[104:107]
	s_waitcnt lgkmcnt(3)
	v_mfma_f32_16x16x32_bf16 v[92:95], v[128:131], v[176:179], v[92:95]
	v_mfma_f32_16x16x32_bf16 v[88:91], v[136:139], v[176:179], v[88:91]
	s_waitcnt lgkmcnt(1)
	v_mfma_f32_16x16x32_bf16 v[76:79], v[128:131], v[184:187], v[76:79]
	v_mfma_f32_16x16x32_bf16 v[72:75], v[136:139], v[184:187], v[72:75]
	v_mfma_f32_16x16x32_bf16 v[124:127], v[132:135], v[164:167], v[124:127]
	v_mfma_f32_16x16x32_bf16 v[120:123], v[140:143], v[164:167], v[120:123]
	v_mfma_f32_16x16x32_bf16 v[108:111], v[132:135], v[172:175], v[108:111]
	v_mfma_f32_16x16x32_bf16 v[104:107], v[140:143], v[172:175], v[104:107]
	v_mfma_f32_16x16x32_bf16 v[92:95], v[132:135], v[180:183], v[92:95]
	v_mfma_f32_16x16x32_bf16 v[88:91], v[140:143], v[180:183], v[88:91]
	s_waitcnt lgkmcnt(0)
	v_mfma_f32_16x16x32_bf16 v[76:79], v[132:135], v[188:191], v[76:79]
	v_mfma_f32_16x16x32_bf16 v[72:75], v[140:143], v[188:191], v[72:75]
	s_barrier
	s_add_i32 s54, s85, 0x100
	v_add_u32_e32 v158, s54, v162
	s_add_i32 s0, s2, s14
	ds_read_b128 v[192:195], v158
	ds_read_b128 v[196:199], v158 offset:1024
	ds_read_b128 v[200:203], v158 offset:2048
	ds_read_b128 v[204:207], v158 offset:3072
	v_lshl_add_u64 v[158:159], s[78:79], 0, v[146:147]
	s_mov_b32 m0, s0
	s_nop 0
	global_load_lds_dwordx4 v[158:159], off
	v_lshl_add_u64 v[158:159], s[78:79], 0, v[152:153]
	s_add_i32 m0, s0, 0x2000
	s_nop 0
	global_load_lds_dwordx4 v[158:159], off
	s_barrier
	s_waitcnt lgkmcnt(0)
	v_mfma_f32_16x16x32_bf16 v[116:119], v[192:195], v[154:157], v[116:119]
	v_mfma_f32_16x16x32_bf16 v[112:115], v[200:203], v[154:157], v[112:115]
	v_mfma_f32_16x16x32_bf16 v[100:103], v[192:195], v[168:171], v[100:103]
	v_mfma_f32_16x16x32_bf16 v[96:99], v[200:203], v[168:171], v[96:99]
	v_mfma_f32_16x16x32_bf16 v[84:87], v[192:195], v[176:179], v[84:87]
	v_mfma_f32_16x16x32_bf16 v[80:83], v[200:203], v[176:179], v[80:83]
	v_mfma_f32_16x16x32_bf16 v[68:71], v[192:195], v[184:187], v[68:71]
	v_mfma_f32_16x16x32_bf16 v[64:67], v[200:203], v[184:187], v[64:67]
	v_mfma_f32_16x16x32_bf16 v[116:119], v[196:199], v[164:167], v[116:119]
	v_mfma_f32_16x16x32_bf16 v[112:115], v[204:207], v[164:167], v[112:115]
	v_mfma_f32_16x16x32_bf16 v[100:103], v[196:199], v[172:175], v[100:103]
	v_mfma_f32_16x16x32_bf16 v[96:99], v[204:207], v[172:175], v[96:99]
	v_mfma_f32_16x16x32_bf16 v[84:87], v[196:199], v[180:183], v[84:87]
	v_mfma_f32_16x16x32_bf16 v[80:83], v[204:207], v[180:183], v[80:83]
	v_mfma_f32_16x16x32_bf16 v[68:71], v[196:199], v[188:191], v[68:71]
	v_mfma_f32_16x16x32_bf16 v[64:67], v[204:207], v[188:191], v[64:67]
	s_mov_b32 m0, s25
	v_lshl_add_u64 v[158:159], s[76:77], 0, v[148:149]
	s_barrier
	ds_read_b128 v[154:157], v163 offset:16384
	ds_read_b128 v[164:167], v163 offset:17408
	ds_read_b128 v[168:171], v163 offset:18432
	ds_read_b128 v[172:175], v163 offset:19456
	ds_read_b128 v[176:179], v163 offset:20480
	ds_read_b128 v[180:183], v163 offset:21504
	ds_read_b128 v[184:187], v163 offset:22528
	ds_read_b128 v[188:191], v163 offset:23552
	global_load_lds_dwordx4 v[158:159], off
	v_lshl_add_u64 v[158:159], s[76:77], 0, v[150:151]
	s_mov_b32 m0, s36
	s_nop 0
	global_load_lds_dwordx4 v[158:159], off
	s_barrier
	s_waitcnt lgkmcnt(0)
	v_mfma_f32_16x16x32_bf16 v[60:63], v[128:131], v[154:157], v[60:63]
	v_mfma_f32_16x16x32_bf16 v[56:59], v[136:139], v[154:157], v[56:59]
	v_mfma_f32_16x16x32_bf16 v[44:47], v[128:131], v[168:171], v[44:47]
	v_mfma_f32_16x16x32_bf16 v[40:43], v[136:139], v[168:171], v[40:43]
	v_mfma_f32_16x16x32_bf16 v[28:31], v[128:131], v[176:179], v[28:31]
	v_mfma_f32_16x16x32_bf16 v[24:27], v[136:139], v[176:179], v[24:27]
	v_mfma_f32_16x16x32_bf16 v[20:23], v[128:131], v[184:187], v[20:23]
	v_mfma_f32_16x16x32_bf16 v[12:15], v[136:139], v[184:187], v[12:15]
	v_mfma_f32_16x16x32_bf16 v[60:63], v[132:135], v[164:167], v[60:63]
	v_mfma_f32_16x16x32_bf16 v[56:59], v[140:143], v[164:167], v[56:59]
	v_mfma_f32_16x16x32_bf16 v[44:47], v[132:135], v[172:175], v[44:47]
	v_mfma_f32_16x16x32_bf16 v[40:43], v[140:143], v[172:175], v[40:43]
	v_mfma_f32_16x16x32_bf16 v[28:31], v[132:135], v[180:183], v[28:31]
	v_mfma_f32_16x16x32_bf16 v[24:27], v[140:143], v[180:183], v[24:27]
	v_mfma_f32_16x16x32_bf16 v[20:23], v[132:135], v[188:191], v[20:23]
	v_mfma_f32_16x16x32_bf16 v[12:15], v[140:143], v[188:191], v[12:15]
	s_barrier
; #define G_STAGE(bufoff, gbase, voff) do { _Pragma("unroll") for (int _i = 0; _i < 2; ++_i) \
;         __builtin_amdgcn_global_load_lds((const unsigned*)((const char*)(gbase) + (voff)[_i]), (LAS unsigned*)(lds + (bufoff) + ldsw + _i * 8192), 16, 0, 0); } while (0)
; #define G_LDA(dst, b, h) do { _Pragma("unroll") for (int m = 0; m < 4; ++m) _Pragma("unroll") for (int k = 0; k < 2; ++k) dst[m][k] = *(const LAS bf16x8*)(lds + G_SA(b, h) + aoff + m * 2048 + k * 1024); } while (0)
; #define G_LDB(dst, b, h) do { _Pragma("unroll") for (int n = 0; n < 2; ++n) _Pragma("unroll") for (int k = 0; k < 2; ++k) dst[n][k] = *(const LAS bf16x8*)(lds + G_SB(b, h) + boff + n * 2048 + k * 1024); } while (0)
; #define G_MMA(ai, bj, At, Bt) do { __builtin_amdgcn_s_setprio(1); _Pragma("unroll") for (int m = 0; m < 4; ++m) _Pragma("unroll") for (int n = 0; n < 2; ++n) _Pragma("unroll") for (int k = 0; k < 2; ++k) \
;         acc[ai][bj][m][n] = __builtin_amdgcn_mfma_f32_16x16x32_bf16(Bt[n][k], At[m][k], acc[ai][bj][m][n], 0, 0, 0); __builtin_amdgcn_s_setprio(0); } while (0)
; #define G_WAIT_V(n) asm volatile("s_waitcnt vmcnt(" #n ")" ::: "memory")
; #define G_WAIT_L(n) asm volatile("s_waitcnt lgkmcnt(" #n ")" ::: "memory")
; #define G_BAR __builtin_amdgcn_s_barrier()
; #define G_SCHED __builtin_amdgcn_sched_barrier(0)
; template <class J>
; DI void gemm_phase(LAS unsigned char* lds, const J& job) {
;     ...
;       G_STAGE(G_SB(0, 1), b2 + hstepB, voffB);
;       G_WAIT_V(6); G_BAR; G_MMA(1, 1, At, B1); G_BAR;
;       G_LDB(B0, 1, 0); G_SCHED; G_LDA(At, 1, 0); G_STAGE(G_SA(0, 1), a2 + hstepA, voffA);
;       G_WAIT_L(8); G_BAR; G_WAIT_L(0); G_MMA(0, 0, At, B0); G_BAR; G_SCHED;
;       G_LDB(B1, 1, 1); G_STAGE(G_SB(1, 0), b3, voffB);
;       G_BAR; G_WAIT_L(0); G_MMA(0, 1, At, B1); G_BAR;
;       G_LDA(At, 1, 1); G_STAGE(G_SA(1, 0), a3, voffA);
	s_add_u32 s0, s78, 0x80000
	s_addc_u32 s1, s79, 0
	s_add_i32 s2, s54, s14
	v_lshl_add_u64 v[128:129], s[0:1], 0, v[146:147]
	s_mov_b32 m0, s2
	s_nop 0
	global_load_lds_dwordx4 v[128:129], off
	v_lshl_add_u64 v[128:129], s[0:1], 0, v[152:153]
	s_add_i32 m0, s2, 0x2000
	s_nop 0
	global_load_lds_dwordx4 v[128:129], off
	s_waitcnt vmcnt(6)
	s_barrier
	v_mfma_f32_16x16x32_bf16 v[52:55], v[192:195], v[154:157], v[52:55]
	v_mfma_f32_16x16x32_bf16 v[48:51], v[200:203], v[154:157], v[48:51]
	v_mfma_f32_16x16x32_bf16 v[36:39], v[192:195], v[168:171], v[36:39]
	v_mfma_f32_16x16x32_bf16 v[32:35], v[200:203], v[168:171], v[32:35]
	v_mfma_f32_16x16x32_bf16 v[16:19], v[192:195], v[176:179], v[16:19]
	v_mfma_f32_16x16x32_bf16 v[8:11], v[200:203], v[176:179], v[8:11]
	v_mfma_f32_16x16x32_bf16 v[4:7], v[192:195], v[184:187], v[4:7]
	v_mfma_f32_16x16x32_bf16 v[0:3], v[200:203], v[184:187], v[0:3]
	v_mfma_f32_16x16x32_bf16 v[52:55], v[196:199], v[164:167], v[52:55]
	v_mfma_f32_16x16x32_bf16 v[48:51], v[204:207], v[164:167], v[48:51]
	v_mfma_f32_16x16x32_bf16 v[36:39], v[196:199], v[172:175], v[36:39]
	v_mfma_f32_16x16x32_bf16 v[32:35], v[204:207], v[172:175], v[32:35]
	v_mfma_f32_16x16x32_bf16 v[16:19], v[196:199], v[180:183], v[16:19]
	v_mfma_f32_16x16x32_bf16 v[8:11], v[204:207], v[180:183], v[8:11]
	v_mfma_f32_16x16x32_bf16 v[4:7], v[196:199], v[188:191], v[4:7]
	v_mfma_f32_16x16x32_bf16 v[0:3], v[204:207], v[188:191], v[0:3]
	s_add_i32 s2, s88, 0x100
	v_add_u32_e32 v140, s2, v162
	s_barrier
	ds_read_b128 v[128:131], v140
	ds_read_b128 v[132:135], v140 offset:1024
	ds_read_b128 v[136:139], v140 offset:2048
	ds_read_b128 v[140:143], v140 offset:3072
	s_add_u32 s0, s76, 0x80000
	s_addc_u32 s1, s77, 0
	s_mov_b32 m0, s37
	v_lshl_add_u64 v[158:159], s[0:1], 0, v[148:149]
	ds_read_b128 v[154:157], v163 offset:32768
	ds_read_b128 v[164:167], v163 offset:33792
	ds_read_b128 v[168:171], v163 offset:34816
	ds_read_b128 v[172:175], v163 offset:35840
	ds_read_b128 v[176:179], v163 offset:36864
	ds_read_b128 v[180:183], v163 offset:37888
	ds_read_b128 v[184:187], v163 offset:38912
	ds_read_b128 v[188:191], v163 offset:39936
	global_load_lds_dwordx4 v[158:159], off
	v_lshl_add_u64 v[158:159], s[0:1], 0, v[150:151]
	s_mov_b32 m0, s38
	s_nop 0
	global_load_lds_dwordx4 v[158:159], off
	s_waitcnt lgkmcnt(8)
	s_barrier
	s_waitcnt lgkmcnt(7)
	v_mfma_f32_16x16x32_bf16 v[124:127], v[128:131], v[154:157], v[124:127]
	v_mfma_f32_16x16x32_bf16 v[120:123], v[136:139], v[154:157], v[120:123]
	s_waitcnt lgkmcnt(5)
	v_mfma_f32_16x16x32_bf16 v[108:111], v[128:131], v[168:171], v[108:111]
	v_mfma_f32_16x16x32_bf16 v[104:107], v[136:139], v[168:171], v[104:107]
	s_waitcnt lgkmcnt(3)
	v_mfma_f32_16x16x32_bf16 v[92:95], v[128:131], v[176:179], v[92:95]
	v_mfma_f32_16x16x32_bf16 v[88:91], v[136:139], v[176:179], v[88:91]
	s_waitcnt lgkmcnt(1)
	v_mfma_f32_16x16x32_bf16 v[76:79], v[128:131], v[184:187], v[76:79]
	v_mfma_f32_16x16x32_bf16 v[72:75], v[136:139], v[184:187], v[72:75]
	v_mfma_f32_16x16x32_bf16 v[124:127], v[132:135], v[164:167], v[124:127]
	v_mfma_f32_16x16x32_bf16 v[120:123], v[140:143], v[164:167], v[120:123]
	v_mfma_f32_16x16x32_bf16 v[108:111], v[132:135], v[172:175], v[108:111]
	v_mfma_f32_16x16x32_bf16 v[104:107], v[140:143], v[172:175], v[104:107]
	v_mfma_f32_16x16x32_bf16 v[92:95], v[132:135], v[180:183], v[92:95]
	v_mfma_f32_16x16x32_bf16 v[88:91], v[140:143], v[180:183], v[88:91]
	s_waitcnt lgkmcnt(0)
	v_mfma_f32_16x16x32_bf16 v[76:79], v[132:135], v[188:191], v[76:79]
	v_mfma_f32_16x16x32_bf16 v[72:75], v[140:143], v[188:191], v[72:75]
	s_barrier
	s_add_i32 s54, s89, 0x100
	v_add_u32_e32 v158, s54, v162
	s_add_i32 s0, s2, s14
	ds_read_b128 v[192:195], v158
	ds_read_b128 v[196:199], v158 offset:1024
	ds_read_b128 v[200:203], v158 offset:2048
	ds_read_b128 v[204:207], v158 offset:3072
	v_lshl_add_u64 v[158:159], s[72:73], 0, v[146:147]
	s_mov_b32 m0, s0
	s_nop 0
	global_load_lds_dwordx4 v[158:159], off
	v_lshl_add_u64 v[158:159], s[72:73], 0, v[152:153]
	s_add_i32 m0, s0, 0x2000
	s_nop 0
	global_load_lds_dwordx4 v[158:159], off
	s_barrier
	s_waitcnt lgkmcnt(0)
	v_mfma_f32_16x16x32_bf16 v[116:119], v[192:195], v[154:157], v[116:119]
	v_mfma_f32_16x16x32_bf16 v[112:115], v[200:203], v[154:157], v[112:115]
	v_mfma_f32_16x16x32_bf16 v[100:103], v[192:195], v[168:171], v[100:103]
	v_mfma_f32_16x16x32_bf16 v[96:99], v[200:203], v[168:171], v[96:99]
	v_mfma_f32_16x16x32_bf16 v[84:87], v[192:195], v[176:179], v[84:87]
	v_mfma_f32_16x16x32_bf16 v[80:83], v[200:203], v[176:179], v[80:83]
	v_mfma_f32_16x16x32_bf16 v[68:71], v[192:195], v[184:187], v[68:71]
	v_mfma_f32_16x16x32_bf16 v[64:67], v[200:203], v[184:187], v[64:67]
	v_mfma_f32_16x16x32_bf16 v[116:119], v[196:199], v[164:167], v[116:119]
	v_mfma_f32_16x16x32_bf16 v[112:115], v[204:207], v[164:167], v[112:115]
	v_mfma_f32_16x16x32_bf16 v[100:103], v[196:199], v[172:175], v[100:103]
	v_mfma_f32_16x16x32_bf16 v[96:99], v[204:207], v[172:175], v[96:99]
	v_mfma_f32_16x16x32_bf16 v[84:87], v[196:199], v[180:183], v[84:87]
	v_mfma_f32_16x16x32_bf16 v[80:83], v[204:207], v[180:183], v[80:83]
	v_mfma_f32_16x16x32_bf16 v[68:71], v[196:199], v[188:191], v[68:71]
	v_mfma_f32_16x16x32_bf16 v[64:67], v[204:207], v[188:191], v[64:67]
	s_mov_b32 m0, s87
	v_lshl_add_u64 v[158:159], s[74:75], 0, v[148:149]
	s_barrier
; #define G_STAGE(bufoff, gbase, voff) do { _Pragma("unroll") for (int _i = 0; _i < 2; ++_i) \
;         __builtin_amdgcn_global_load_lds((const unsigned*)((const char*)(gbase) + (voff)[_i]), (LAS unsigned*)(lds + (bufoff) + ldsw + _i * 8192), 16, 0, 0); } while (0)
; #define G_LDA(dst, b, h) do { _Pragma("unroll") for (int m = 0; m < 4; ++m) _Pragma("unroll") for (int k = 0; k < 2; ++k) dst[m][k] = *(const LAS bf16x8*)(lds + G_SA(b, h) + aoff + m * 2048 + k * 1024); } while (0)
; #define G_MMA(ai, bj, At, Bt) do { __builtin_amdgcn_s_setprio(1); _Pragma("unroll") for (int m = 0; m < 4; ++m) _Pragma("unroll") for (int n = 0; n < 2; ++n) _Pragma("unroll") for (int k = 0; k < 2; ++k) \
;         acc[ai][bj][m][n] = __builtin_amdgcn_mfma_f32_16x16x32_bf16(Bt[n][k], At[m][k], acc[ai][bj][m][n], 0, 0, 0); __builtin_amdgcn_s_setprio(0); } while (0)
; #define G_WAIT_V(n) asm volatile("s_waitcnt vmcnt(" #n ")" ::: "memory")
; #define G_WAIT_L(n) asm volatile("s_waitcnt lgkmcnt(" #n ")" ::: "memory")
; #define G_BAR __builtin_amdgcn_s_barrier()
; #define G_SCHED __builtin_amdgcn_sched_barrier(0)
; template <class J>
; DI void gemm_phase(LAS unsigned char* lds, const J& job) {
;     ...
;       G_LDA(At, 1, 1); G_STAGE(G_SA(1, 0), a3, voffA);
;       G_BAR; G_WAIT_L(0); G_MMA(1, 0, At, B0); G_BAR; G_SCHED;
;       G_STAGE(G_SB(1, 1), b3 + hstepB, voffB);
;       G_WAIT_V(6); G_BAR; G_MMA(1, 1, At, B1); G_BAR;
;   DI void epi(const Acc& acc, const Unit& u, int wr, int wc, int fr, int fq) const {
; #pragma unroll
;     for (int ai = 0; ai < 2; ++ai) {
;       f32x4 res[4][2][2];
; #pragma unroll
;       for (int m = 0; m < 4; ++m) {
;         const int row = u.pm * 256 + ai * HALF + wr * 64 + m * 16 + fr;
;         const float* src = (l == 0) ? xp + (size_t)row * DM : out + (size_t)row * DM;
; #pragma unroll
;         for (int bj = 0; bj < 2; ++bj) { const int col = u.pn * 256 + bj * HALF + wc * 32 + 8 * fq; res[m][bj][0] = *(const f32x4*)(src + col); res[m][bj][1] = *(const f32x4*)(src + col + 4); }
;       }
	ds_read_b128 v[154:157], v163 offset:49152
	ds_read_b128 v[164:167], v163 offset:50176
	ds_read_b128 v[168:171], v163 offset:51200
	ds_read_b128 v[172:175], v163 offset:52224
	ds_read_b128 v[176:179], v163 offset:53248
	ds_read_b128 v[180:183], v163 offset:54272
	ds_read_b128 v[184:187], v163 offset:55296
	ds_read_b128 v[188:191], v163 offset:56320
	global_load_lds_dwordx4 v[158:159], off
	v_lshl_add_u64 v[158:159], s[74:75], 0, v[150:151]
	s_mov_b32 m0, s94
	s_nop 0
	global_load_lds_dwordx4 v[158:159], off
	s_barrier
	s_waitcnt lgkmcnt(0)
	v_mfma_f32_16x16x32_bf16 v[60:63], v[128:131], v[154:157], v[60:63]
	v_mfma_f32_16x16x32_bf16 v[56:59], v[136:139], v[154:157], v[56:59]
	v_mfma_f32_16x16x32_bf16 v[44:47], v[128:131], v[168:171], v[44:47]
	v_mfma_f32_16x16x32_bf16 v[40:43], v[136:139], v[168:171], v[40:43]
	v_mfma_f32_16x16x32_bf16 v[28:31], v[128:131], v[176:179], v[28:31]
	v_mfma_f32_16x16x32_bf16 v[24:27], v[136:139], v[176:179], v[24:27]
	v_mfma_f32_16x16x32_bf16 v[20:23], v[128:131], v[184:187], v[20:23]
	v_mfma_f32_16x16x32_bf16 v[12:15], v[136:139], v[184:187], v[12:15]
	v_mfma_f32_16x16x32_bf16 v[60:63], v[132:135], v[164:167], v[60:63]
	v_mfma_f32_16x16x32_bf16 v[56:59], v[140:143], v[164:167], v[56:59]
	v_mfma_f32_16x16x32_bf16 v[44:47], v[132:135], v[172:175], v[44:47]
	v_mfma_f32_16x16x32_bf16 v[40:43], v[140:143], v[172:175], v[40:43]
	v_mfma_f32_16x16x32_bf16 v[28:31], v[132:135], v[180:183], v[28:31]
	v_mfma_f32_16x16x32_bf16 v[24:27], v[140:143], v[180:183], v[24:27]
	v_mfma_f32_16x16x32_bf16 v[20:23], v[132:135], v[188:191], v[20:23]
	v_mfma_f32_16x16x32_bf16 v[12:15], v[140:143], v[188:191], v[12:15]
	s_barrier
	s_add_u32 s0, s72, 0x80000
	s_addc_u32 s1, s73, 0
	s_add_i32 s2, s54, s14
	v_lshl_add_u64 v[128:129], s[0:1], 0, v[146:147]
	s_mov_b32 m0, s2
	s_nop 0
	global_load_lds_dwordx4 v[128:129], off
	v_lshl_add_u64 v[128:129], s[0:1], 0, v[152:153]
	s_add_i32 m0, s2, 0x2000
	s_nop 0
	global_load_lds_dwordx4 v[128:129], off
	s_waitcnt vmcnt(6)
	s_barrier
	v_mfma_f32_16x16x32_bf16 v[52:55], v[192:195], v[154:157], v[52:55]
	v_mfma_f32_16x16x32_bf16 v[48:51], v[200:203], v[154:157], v[48:51]
	v_mfma_f32_16x16x32_bf16 v[36:39], v[192:195], v[168:171], v[36:39]
	v_mfma_f32_16x16x32_bf16 v[32:35], v[200:203], v[168:171], v[32:35]
	v_mfma_f32_16x16x32_bf16 v[16:19], v[192:195], v[176:179], v[16:19]
	v_mfma_f32_16x16x32_bf16 v[8:11], v[200:203], v[176:179], v[8:11]
	v_mfma_f32_16x16x32_bf16 v[4:7], v[192:195], v[184:187], v[4:7]
	v_mfma_f32_16x16x32_bf16 v[0:3], v[200:203], v[184:187], v[0:3]
	v_mfma_f32_16x16x32_bf16 v[52:55], v[196:199], v[164:167], v[52:55]
	v_mfma_f32_16x16x32_bf16 v[48:51], v[204:207], v[164:167], v[48:51]
	v_mfma_f32_16x16x32_bf16 v[36:39], v[196:199], v[172:175], v[36:39]
	v_mfma_f32_16x16x32_bf16 v[32:35], v[204:207], v[172:175], v[32:35]
	v_mfma_f32_16x16x32_bf16 v[16:19], v[196:199], v[180:183], v[16:19]
	v_mfma_f32_16x16x32_bf16 v[8:11], v[204:207], v[180:183], v[8:11]
	v_mfma_f32_16x16x32_bf16 v[4:7], v[196:199], v[188:191], v[4:7]
	v_mfma_f32_16x16x32_bf16 v[0:3], v[204:207], v[188:191], v[0:3]
	s_add_i32 s7, s7, 2
	s_addk_i32 s57, 0x100
	s_addk_i32 s44, 0x100
	s_cmp_gt_u32 s7, 29
	s_barrier
	s_cbranch_scc0 .LBB0_42
	s_lshl_b32 s0, s66, 8
	v_mov_b32_e32 v128, v161
	v_mov_b32_e32 v129, v160
	s_add_i32 s0, s0, s67
	s_and_b64 vcc, exec, s[18:19]
	v_add_u32_e32 v156, s0, v129
	s_lshl_b32 s0, s46, 8
	s_or_b32 s0, s0, s83
	v_lshl_add_u32 v128, v128, 3, s0
	v_ashrrev_i32_e32 v157, 31, v156
	v_ashrrev_i32_e32 v129, 31, v128
	v_lshlrev_b64 v[212:213], 13, v[156:157]
	v_lshl_add_u64 v[130:131], s[8:9], 0, v[212:213]
	v_lshlrev_b64 v[154:155], 2, v[128:129]
	v_lshl_add_u64 v[128:129], v[130:131], 0, v[154:155]
	global_load_dwordx4 v[164:167], v[128:129], off offset:16
	global_load_dwordx4 v[168:171], v[128:129], off
	global_load_dwordx4 v[172:175], v[128:129], off offset:528
	global_load_dwordx4 v[176:179], v[128:129], off offset:512
	v_add_u32_e32 v128, 16, v156
	v_ashrrev_i32_e32 v129, 31, v128
	v_lshlrev_b64 v[214:215], 13, v[128:129]
	v_lshl_add_u64 v[128:129], s[8:9], 0, v[214:215]
	v_lshl_add_u64 v[128:129], v[128:129], 0, v[154:155]
	global_load_dwordx4 v[180:183], v[128:129], off offset:16
	global_load_dwordx4 v[184:187], v[128:129], off
	global_load_dwordx4 v[188:191], v[128:129], off offset:528
	global_load_dwordx4 v[192:195], v[128:129], off offset:512
	v_add_u32_e32 v128, 32, v156
	v_ashrrev_i32_e32 v129, 31, v128
	v_lshlrev_b64 v[216:217], 13, v[128:129]
	v_lshl_add_u64 v[128:129], s[8:9], 0, v[216:217]
	v_lshl_add_u64 v[128:129], v[128:129], 0, v[154:155]
	global_load_dwordx4 v[196:199], v[128:129], off offset:16
	global_load_dwordx4 v[200:203], v[128:129], off
	global_load_dwordx4 v[204:207], v[128:129], off offset:528
	global_load_dwordx4 v[208:211], v[128:129], off offset:512
	v_add_u32_e32 v128, 48, v156
	v_ashrrev_i32_e32 v129, 31, v128
	v_lshlrev_b64 v[158:159], 13, v[128:129]
	v_lshl_add_u64 v[128:129], s[8:9], 0, v[158:159]
	v_lshl_add_u64 v[136:137], v[128:129], 0, v[154:155]
	global_load_dwordx4 v[132:135], v[136:137], off offset:16
	global_load_dwordx4 v[140:143], v[136:137], off
	global_load_dwordx4 v[128:131], v[136:137], off offset:528
	s_nop 0
	global_load_dwordx4 v[136:139], v[136:137], off offset:512
	v_lshl_add_u64 v[212:213], s[16:17], 0, v[212:213]
	s_mov_b32 s46, s22
	s_mov_b32 s66, s20
	s_mov_b64 s[68:69], s[64:65]
	s_mov_b64 s[70:71], s[62:63]
	s_movk_i32 s54, 0x4000
	s_movk_i32 s55, 0x6000
	v_readlane_b32 s0, v255, 23
	s_cmpk_gt_u32 s0, 0xff
	s_cbranch_scc1 .Lds_out_x
	s_barrier

; #define G_STAGE(bufoff, gbase, voff) do { _Pragma("unroll") for (int _i = 0; _i < 2; ++_i) \
;         __builtin_amdgcn_global_load_lds((const unsigned*)((const char*)(gbase) + (voff)[_i]), (LAS unsigned*)(lds + (bufoff) + ldsw + _i * 8192), 16, 0, 0); } while (0)
; #define G_LDA(dst, b, h) do { _Pragma("unroll") for (int m = 0; m < 4; ++m) _Pragma("unroll") for (int k = 0; k < 2; ++k) dst[m][k] = *(const LAS bf16x8*)(lds + G_SA(b, h) + aoff + m * 2048 + k * 1024); } while (0)
; #define G_LDB(dst, b, h) do { _Pragma("unroll") for (int n = 0; n < 2; ++n) _Pragma("unroll") for (int k = 0; k < 2; ++k) dst[n][k] = *(const LAS bf16x8*)(lds + G_SB(b, h) + boff + n * 2048 + k * 1024); } while (0)
; #define G_MMA(ai, bj, At, Bt) do { __builtin_amdgcn_s_setprio(1); _Pragma("unroll") for (int m = 0; m < 4; ++m) _Pragma("unroll") for (int n = 0; n < 2; ++n) _Pragma("unroll") for (int k = 0; k < 2; ++k) \
;         acc[ai][bj][m][n] = __builtin_amdgcn_mfma_f32_16x16x32_bf16(Bt[n][k], At[m][k], acc[ai][bj][m][n], 0, 0, 0); __builtin_amdgcn_s_setprio(0); } while (0)
; #define G_WAIT_L(n) asm volatile("s_waitcnt lgkmcnt(" #n ")" ::: "memory")
; #define G_BAR __builtin_amdgcn_s_barrier()
; #define G_SCHED __builtin_amdgcn_sched_barrier(0)
; template <class J>
; DI void gemm_phase(LAS unsigned char* lds, const J& job) {
;     ...
;     for (int t = 0; t < nt; t += 2) {
;       const bool last = (t == nt - 2);
;       const char* a1 = cA + G_KT(t + 1);
;       const char* a2 = last ? nA + G_KT(0) : cA + G_KT(t + 2); const char* b2 = last ? nB + G_KT(0) : cB + G_KT(t + 2);
;       const char* a3 = last ? nA + G_KT(1) : cA + G_KT(t + 3); const char* b3 = last ? nB + G_KT(1) : cB + G_KT(t + 3);
;       G_LDB(B0, 0, 0); G_SCHED; G_LDA(At, 0, 0); G_STAGE(G_SA(1, 1), a1 + hstepA, voffA);
;       G_WAIT_L(8); G_BAR; G_WAIT_L(0); G_MMA(0, 0, At, B0); G_BAR; G_SCHED;
;       G_LDB(B1, 0, 1); G_STAGE(G_SB(0, 0), b2, voffB);
;       G_BAR; G_WAIT_L(0); G_MMA(0, 1, At, B1); G_BAR;
;       G_LDA(At, 0, 1); G_STAGE(G_SA(0, 0), a2, voffA);
;       G_BAR; G_WAIT_L(0); G_MMA(1, 0, At, B0); G_BAR; G_SCHED;
.LBB0_74:
	s_add_i32 s1, s56, 0xffffff80
	s_and_b32 s0, s7, 0xf80
	s_and_b32 s1, s1, 0xf00
	s_add_u32 s57, s68, s1
	s_addc_u32 s70, s69, 0
	s_add_u32 s1, s66, s1
	s_addc_u32 s71, s67, 0
	s_and_b32 s72, s56, 0xf80
	s_add_u32 s80, s68, s72
	s_addc_u32 s73, s69, 0
	s_add_u32 s38, s66, s72
	s_addc_u32 s2, s67, 0
	s_cmp_eq_u32 s6, 28
	s_cselect_b32 s75, s46, s70
	s_cselect_b32 s74, s45, s57
	s_cselect_b32 s77, vcc_lo, s71
	s_cselect_b32 s76, s47, s1
	s_cselect_b32 s73, s97, s73
	s_cselect_b32 s72, s33, s80
	s_cselect_b32 s71, s5, s2
	s_cselect_b32 s70, vcc_hi, s38
	s_add_i32 s2, s84, 0x100
	v_add_u32_e32 v100, s2, v248
	ds_read_b128 v[84:87], v100
	ds_read_b128 v[88:91], v100 offset:1024
	ds_read_b128 v[96:99], v100 offset:2048
	ds_read_b128 v[100:103], v100 offset:3072
	s_add_u32 s0, s19, s0
	s_addc_u32 s1, s21, 0
	v_lshl_add_u64 v[186:187], s[0:1], 0, v[148:149]
	s_add_i32 m0, s14, 0xc000
	ds_read_b128 v[154:157], v249
	ds_read_b128 v[158:161], v249 offset:1024
	ds_read_b128 v[162:165], v249 offset:2048
	ds_read_b128 v[166:169], v249 offset:3072
	ds_read_b128 v[170:173], v249 offset:4096
	ds_read_b128 v[174:177], v249 offset:5120
	ds_read_b128 v[178:181], v249 offset:6144
	ds_read_b128 v[182:185], v249 offset:7168
	global_load_lds_dwordx4 v[186:187], off
	v_lshl_add_u64 v[186:187], s[0:1], 0, v[150:151]
	s_add_i32 m0, s14, 0xe000
	s_nop 0
	global_load_lds_dwordx4 v[186:187], off
	s_waitcnt lgkmcnt(8)
	s_barrier
	s_waitcnt lgkmcnt(7)
	v_mfma_f32_16x16x32_bf16 v[140:143], v[84:87], v[154:157], v[140:143]
	v_mfma_f32_16x16x32_bf16 v[136:139], v[96:99], v[154:157], v[136:139]
	s_waitcnt lgkmcnt(5)
	v_mfma_f32_16x16x32_bf16 v[124:127], v[84:87], v[162:165], v[124:127]
	v_mfma_f32_16x16x32_bf16 v[120:123], v[96:99], v[162:165], v[120:123]
	s_waitcnt lgkmcnt(3)
	v_mfma_f32_16x16x32_bf16 v[108:111], v[84:87], v[170:173], v[108:111]
	v_mfma_f32_16x16x32_bf16 v[104:107], v[96:99], v[170:173], v[104:107]
	s_waitcnt lgkmcnt(1)
	v_mfma_f32_16x16x32_bf16 v[76:79], v[84:87], v[178:181], v[76:79]
	v_mfma_f32_16x16x32_bf16 v[72:75], v[96:99], v[178:181], v[72:75]
	v_mfma_f32_16x16x32_bf16 v[140:143], v[88:91], v[158:161], v[140:143]
	v_mfma_f32_16x16x32_bf16 v[136:139], v[100:103], v[158:161], v[136:139]
	v_mfma_f32_16x16x32_bf16 v[124:127], v[88:91], v[166:169], v[124:127]
	v_mfma_f32_16x16x32_bf16 v[120:123], v[100:103], v[166:169], v[120:123]
	v_mfma_f32_16x16x32_bf16 v[108:111], v[88:91], v[174:177], v[108:111]
	v_mfma_f32_16x16x32_bf16 v[104:107], v[100:103], v[174:177], v[104:107]
	s_waitcnt lgkmcnt(0)
	v_mfma_f32_16x16x32_bf16 v[76:79], v[88:91], v[182:185], v[76:79]
	v_mfma_f32_16x16x32_bf16 v[72:75], v[100:103], v[182:185], v[72:75]
	s_barrier
	s_add_i32 s38, s85, 0x100
	s_add_i32 s0, s2, s78
	v_add_u32_e32 v198, s38, v248
	v_lshl_add_u64 v[202:203], s[76:77], 0, v[146:147]
	s_mov_b32 m0, s0
	ds_read_b128 v[186:189], v198
	ds_read_b128 v[190:193], v198 offset:1024
	ds_read_b128 v[194:197], v198 offset:2048
	ds_read_b128 v[198:201], v198 offset:3072
	global_load_lds_dwordx4 v[202:203], off
	v_lshl_add_u64 v[202:203], s[76:77], 0, v[152:153]
	s_add_i32 m0, s0, 0x2000
	s_nop 0
	global_load_lds_dwordx4 v[202:203], off
	s_barrier
	s_waitcnt lgkmcnt(0)
	v_mfma_f32_16x16x32_bf16 v[132:135], v[186:189], v[154:157], v[132:135]
	v_mfma_f32_16x16x32_bf16 v[128:131], v[194:197], v[154:157], v[128:131]
	v_mfma_f32_16x16x32_bf16 v[116:119], v[186:189], v[162:165], v[116:119]
	v_mfma_f32_16x16x32_bf16 v[112:115], v[194:197], v[162:165], v[112:115]
	v_mfma_f32_16x16x32_bf16 v[92:95], v[186:189], v[170:173], v[92:95]
	v_mfma_f32_16x16x32_bf16 v[80:83], v[194:197], v[170:173], v[80:83]
	v_mfma_f32_16x16x32_bf16 v[68:71], v[186:189], v[178:181], v[68:71]
	v_mfma_f32_16x16x32_bf16 v[64:67], v[194:197], v[178:181], v[64:67]
	v_mfma_f32_16x16x32_bf16 v[132:135], v[190:193], v[158:161], v[132:135]
	v_mfma_f32_16x16x32_bf16 v[128:131], v[198:201], v[158:161], v[128:131]
	v_mfma_f32_16x16x32_bf16 v[116:119], v[190:193], v[166:169], v[116:119]
	v_mfma_f32_16x16x32_bf16 v[112:115], v[198:201], v[166:169], v[112:115]
	v_mfma_f32_16x16x32_bf16 v[92:95], v[190:193], v[174:177], v[92:95]
	v_mfma_f32_16x16x32_bf16 v[80:83], v[198:201], v[174:177], v[80:83]
	v_mfma_f32_16x16x32_bf16 v[68:71], v[190:193], v[182:185], v[68:71]
	v_mfma_f32_16x16x32_bf16 v[64:67], v[198:201], v[182:185], v[64:67]
	s_mov_b32 m0, s14
	v_lshl_add_u64 v[202:203], s[74:75], 0, v[148:149]
	s_barrier
	ds_read_b128 v[154:157], v249 offset:16384
	ds_read_b128 v[158:161], v249 offset:17408
	ds_read_b128 v[162:165], v249 offset:18432
	ds_read_b128 v[166:169], v249 offset:19456
	ds_read_b128 v[170:173], v249 offset:20480
	ds_read_b128 v[174:177], v249 offset:21504
	ds_read_b128 v[178:181], v249 offset:22528
	ds_read_b128 v[182:185], v249 offset:23552
	global_load_lds_dwordx4 v[202:203], off
	v_lshl_add_u64 v[202:203], s[74:75], 0, v[150:151]
	s_mov_b32 m0, s15
	s_nop 0
	global_load_lds_dwordx4 v[202:203], off
	s_barrier
	s_waitcnt lgkmcnt(0)
	v_mfma_f32_16x16x32_bf16 v[60:63], v[84:87], v[154:157], v[60:63]
	v_mfma_f32_16x16x32_bf16 v[56:59], v[96:99], v[154:157], v[56:59]
	v_mfma_f32_16x16x32_bf16 v[44:47], v[84:87], v[162:165], v[44:47]
	v_mfma_f32_16x16x32_bf16 v[40:43], v[96:99], v[162:165], v[40:43]
	v_mfma_f32_16x16x32_bf16 v[28:31], v[84:87], v[170:173], v[28:31]
	v_mfma_f32_16x16x32_bf16 v[24:27], v[96:99], v[170:173], v[24:27]
	v_mfma_f32_16x16x32_bf16 v[12:15], v[84:87], v[178:181], v[12:15]
	v_mfma_f32_16x16x32_bf16 v[8:11], v[96:99], v[178:181], v[8:11]
	v_mfma_f32_16x16x32_bf16 v[60:63], v[88:91], v[158:161], v[60:63]
	v_mfma_f32_16x16x32_bf16 v[56:59], v[100:103], v[158:161], v[56:59]
	v_mfma_f32_16x16x32_bf16 v[44:47], v[88:91], v[166:169], v[44:47]
	v_mfma_f32_16x16x32_bf16 v[40:43], v[100:103], v[166:169], v[40:43]
	v_mfma_f32_16x16x32_bf16 v[28:31], v[88:91], v[174:177], v[28:31]
	v_mfma_f32_16x16x32_bf16 v[24:27], v[100:103], v[174:177], v[24:27]
	v_mfma_f32_16x16x32_bf16 v[12:15], v[88:91], v[182:185], v[12:15]
	v_mfma_f32_16x16x32_bf16 v[8:11], v[100:103], v[182:185], v[8:11]
	s_barrier
; #define G_STAGE(bufoff, gbase, voff) do { _Pragma("unroll") for (int _i = 0; _i < 2; ++_i) \
;         __builtin_amdgcn_global_load_lds((const unsigned*)((const char*)(gbase) + (voff)[_i]), (LAS unsigned*)(lds + (bufoff) + ldsw + _i * 8192), 16, 0, 0); } while (0)
; #define G_LDA(dst, b, h) do { _Pragma("unroll") for (int m = 0; m < 4; ++m) _Pragma("unroll") for (int k = 0; k < 2; ++k) dst[m][k] = *(const LAS bf16x8*)(lds + G_SA(b, h) + aoff + m * 2048 + k * 1024); } while (0)
; #define G_LDB(dst, b, h) do { _Pragma("unroll") for (int n = 0; n < 2; ++n) _Pragma("unroll") for (int k = 0; k < 2; ++k) dst[n][k] = *(const LAS bf16x8*)(lds + G_SB(b, h) + boff + n * 2048 + k * 1024); } while (0)
; #define G_MMA(ai, bj, At, Bt) do { __builtin_amdgcn_s_setprio(1); _Pragma("unroll") for (int m = 0; m < 4; ++m) _Pragma("unroll") for (int n = 0; n < 2; ++n) _Pragma("unroll") for (int k = 0; k < 2; ++k) \
;         acc[ai][bj][m][n] = __builtin_amdgcn_mfma_f32_16x16x32_bf16(Bt[n][k], At[m][k], acc[ai][bj][m][n], 0, 0, 0); __builtin_amdgcn_s_setprio(0); } while (0)
; #define G_WAIT_V(n) asm volatile("s_waitcnt vmcnt(" #n ")" ::: "memory")
; #define G_WAIT_L(n) asm volatile("s_waitcnt lgkmcnt(" #n ")" ::: "memory")
; #define G_BAR __builtin_amdgcn_s_barrier()
; #define G_SCHED __builtin_amdgcn_sched_barrier(0)
; template <class J>
; DI void gemm_phase(LAS unsigned char* lds, const J& job) {
;     ...
;       G_STAGE(G_SB(0, 1), b2 + hstepB, voffB);
;       G_WAIT_V(6); G_BAR; G_MMA(1, 1, At, B1); G_BAR;
;       G_LDB(B0, 1, 0); G_SCHED; G_LDA(At, 1, 0); G_STAGE(G_SA(0, 1), a2 + hstepA, voffA);
;       G_WAIT_L(8); G_BAR; G_WAIT_L(0); G_MMA(0, 0, At, B0); G_BAR; G_SCHED;
;       G_LDB(B1, 1, 1); G_STAGE(G_SB(1, 0), b3, voffB);
;       G_BAR; G_WAIT_L(0); G_MMA(0, 1, At, B1); G_BAR;
;       G_LDA(At, 1, 1); G_STAGE(G_SA(1, 0), a3, voffA);
	s_add_u32 s0, s76, 0x1000000
	s_addc_u32 s1, s77, 0
	s_add_i32 s2, s38, s78
	v_lshl_add_u64 v[84:85], s[0:1], 0, v[146:147]
	s_mov_b32 m0, s2
	s_nop 0
	global_load_lds_dwordx4 v[84:85], off
	v_lshl_add_u64 v[84:85], s[0:1], 0, v[152:153]
	s_add_i32 m0, s2, 0x2000
	s_nop 0
	global_load_lds_dwordx4 v[84:85], off
	s_waitcnt vmcnt(6)
	s_barrier
	v_mfma_f32_16x16x32_bf16 v[52:55], v[186:189], v[154:157], v[52:55]
	v_mfma_f32_16x16x32_bf16 v[48:51], v[194:197], v[154:157], v[48:51]
	v_mfma_f32_16x16x32_bf16 v[36:39], v[186:189], v[162:165], v[36:39]
	v_mfma_f32_16x16x32_bf16 v[32:35], v[194:197], v[162:165], v[32:35]
	v_mfma_f32_16x16x32_bf16 v[20:23], v[186:189], v[170:173], v[20:23]
	v_mfma_f32_16x16x32_bf16 v[16:19], v[194:197], v[170:173], v[16:19]
	v_mfma_f32_16x16x32_bf16 v[4:7], v[186:189], v[178:181], v[4:7]
	v_mfma_f32_16x16x32_bf16 v[0:3], v[194:197], v[178:181], v[0:3]
	v_mfma_f32_16x16x32_bf16 v[52:55], v[190:193], v[158:161], v[52:55]
	v_mfma_f32_16x16x32_bf16 v[48:51], v[198:201], v[158:161], v[48:51]
	v_mfma_f32_16x16x32_bf16 v[36:39], v[190:193], v[166:169], v[36:39]
	v_mfma_f32_16x16x32_bf16 v[32:35], v[198:201], v[166:169], v[32:35]
	v_mfma_f32_16x16x32_bf16 v[20:23], v[190:193], v[174:177], v[20:23]
	v_mfma_f32_16x16x32_bf16 v[16:19], v[198:201], v[174:177], v[16:19]
	v_mfma_f32_16x16x32_bf16 v[4:7], v[190:193], v[182:185], v[4:7]
	v_mfma_f32_16x16x32_bf16 v[0:3], v[198:201], v[182:185], v[0:3]
	s_add_i32 s2, s88, 0x100
	v_add_u32_e32 v100, s2, v248
	s_barrier
	ds_read_b128 v[84:87], v100
	ds_read_b128 v[88:91], v100 offset:1024
	ds_read_b128 v[96:99], v100 offset:2048
	ds_read_b128 v[100:103], v100 offset:3072
	s_add_u32 s0, s74, 0x80000
	s_addc_u32 s1, s75, 0
	s_mov_b32 m0, s83
	v_lshl_add_u64 v[186:187], s[0:1], 0, v[148:149]
	ds_read_b128 v[154:157], v249 offset:32768
	ds_read_b128 v[158:161], v249 offset:33792
	ds_read_b128 v[162:165], v249 offset:34816
	ds_read_b128 v[166:169], v249 offset:35840
	ds_read_b128 v[170:173], v249 offset:36864
	ds_read_b128 v[174:177], v249 offset:37888
	ds_read_b128 v[178:181], v249 offset:38912
	ds_read_b128 v[182:185], v249 offset:39936
	global_load_lds_dwordx4 v[186:187], off
	v_lshl_add_u64 v[186:187], s[0:1], 0, v[150:151]
	s_mov_b32 m0, s36
	s_nop 0
	global_load_lds_dwordx4 v[186:187], off
	s_waitcnt lgkmcnt(8)
	s_barrier
	s_waitcnt lgkmcnt(7)
	v_mfma_f32_16x16x32_bf16 v[140:143], v[84:87], v[154:157], v[140:143]
	v_mfma_f32_16x16x32_bf16 v[136:139], v[96:99], v[154:157], v[136:139]
	s_waitcnt lgkmcnt(5)
	v_mfma_f32_16x16x32_bf16 v[124:127], v[84:87], v[162:165], v[124:127]
	v_mfma_f32_16x16x32_bf16 v[120:123], v[96:99], v[162:165], v[120:123]
	s_waitcnt lgkmcnt(3)
	v_mfma_f32_16x16x32_bf16 v[108:111], v[84:87], v[170:173], v[108:111]
	v_mfma_f32_16x16x32_bf16 v[104:107], v[96:99], v[170:173], v[104:107]
	s_waitcnt lgkmcnt(1)
	v_mfma_f32_16x16x32_bf16 v[76:79], v[84:87], v[178:181], v[76:79]
	v_mfma_f32_16x16x32_bf16 v[72:75], v[96:99], v[178:181], v[72:75]
	v_mfma_f32_16x16x32_bf16 v[140:143], v[88:91], v[158:161], v[140:143]
	v_mfma_f32_16x16x32_bf16 v[136:139], v[100:103], v[158:161], v[136:139]
	v_mfma_f32_16x16x32_bf16 v[124:127], v[88:91], v[166:169], v[124:127]
	v_mfma_f32_16x16x32_bf16 v[120:123], v[100:103], v[166:169], v[120:123]
	v_mfma_f32_16x16x32_bf16 v[108:111], v[88:91], v[174:177], v[108:111]
	v_mfma_f32_16x16x32_bf16 v[104:107], v[100:103], v[174:177], v[104:107]
	s_waitcnt lgkmcnt(0)
	v_mfma_f32_16x16x32_bf16 v[76:79], v[88:91], v[182:185], v[76:79]
	v_mfma_f32_16x16x32_bf16 v[72:75], v[100:103], v[182:185], v[72:75]
	s_barrier
	s_add_i32 s38, s89, 0x100
	s_add_i32 s0, s2, s78
	v_add_u32_e32 v198, s38, v248
	v_lshl_add_u64 v[202:203], s[70:71], 0, v[146:147]
	s_mov_b32 m0, s0
	ds_read_b128 v[186:189], v198
	ds_read_b128 v[190:193], v198 offset:1024
	ds_read_b128 v[194:197], v198 offset:2048
	ds_read_b128 v[198:201], v198 offset:3072
	global_load_lds_dwordx4 v[202:203], off
	v_lshl_add_u64 v[202:203], s[70:71], 0, v[152:153]
	s_add_i32 m0, s0, 0x2000
	s_nop 0
	global_load_lds_dwordx4 v[202:203], off
	s_barrier
	s_waitcnt lgkmcnt(0)
	v_mfma_f32_16x16x32_bf16 v[132:135], v[186:189], v[154:157], v[132:135]
	v_mfma_f32_16x16x32_bf16 v[128:131], v[194:197], v[154:157], v[128:131]
	v_mfma_f32_16x16x32_bf16 v[116:119], v[186:189], v[162:165], v[116:119]
	v_mfma_f32_16x16x32_bf16 v[112:115], v[194:197], v[162:165], v[112:115]
	v_mfma_f32_16x16x32_bf16 v[92:95], v[186:189], v[170:173], v[92:95]
	v_mfma_f32_16x16x32_bf16 v[80:83], v[194:197], v[170:173], v[80:83]
	v_mfma_f32_16x16x32_bf16 v[68:71], v[186:189], v[178:181], v[68:71]
	v_mfma_f32_16x16x32_bf16 v[64:67], v[194:197], v[178:181], v[64:67]
	v_mfma_f32_16x16x32_bf16 v[132:135], v[190:193], v[158:161], v[132:135]
	v_mfma_f32_16x16x32_bf16 v[128:131], v[198:201], v[158:161], v[128:131]
	v_mfma_f32_16x16x32_bf16 v[116:119], v[190:193], v[166:169], v[116:119]
	v_mfma_f32_16x16x32_bf16 v[112:115], v[198:201], v[166:169], v[112:115]
	v_mfma_f32_16x16x32_bf16 v[92:95], v[190:193], v[174:177], v[92:95]
	v_mfma_f32_16x16x32_bf16 v[80:83], v[198:201], v[174:177], v[80:83]
	v_mfma_f32_16x16x32_bf16 v[68:71], v[190:193], v[182:185], v[68:71]
	v_mfma_f32_16x16x32_bf16 v[64:67], v[198:201], v[182:185], v[64:67]
	s_mov_b32 m0, s24
	v_lshl_add_u64 v[202:203], s[72:73], 0, v[148:149]
	s_barrier
	ds_read_b128 v[154:157], v249 offset:49152
	ds_read_b128 v[158:161], v249 offset:50176
	ds_read_b128 v[162:165], v249 offset:51200
	ds_read_b128 v[166:169], v249 offset:52224
	ds_read_b128 v[170:173], v249 offset:53248
	ds_read_b128 v[174:177], v249 offset:54272
	ds_read_b128 v[178:181], v249 offset:55296
	ds_read_b128 v[182:185], v249 offset:56320
	global_load_lds_dwordx4 v[202:203], off
	v_lshl_add_u64 v[202:203], s[72:73], 0, v[150:151]
	s_mov_b32 m0, s25
	s_nop 0
	global_load_lds_dwordx4 v[202:203], off
	s_barrier
; #define G_STAGE(bufoff, gbase, voff) do { _Pragma("unroll") for (int _i = 0; _i < 2; ++_i) \
;         __builtin_amdgcn_global_load_lds((const unsigned*)((const char*)(gbase) + (voff)[_i]), (LAS unsigned*)(lds + (bufoff) + ldsw + _i * 8192), 16, 0, 0); } while (0)
; #define G_MMA(ai, bj, At, Bt) do { __builtin_amdgcn_s_setprio(1); _Pragma("unroll") for (int m = 0; m < 4; ++m) _Pragma("unroll") for (int n = 0; n < 2; ++n) _Pragma("unroll") for (int k = 0; k < 2; ++k) \
;         acc[ai][bj][m][n] = __builtin_amdgcn_mfma_f32_16x16x32_bf16(Bt[n][k], At[m][k], acc[ai][bj][m][n], 0, 0, 0); __builtin_amdgcn_s_setprio(0); } while (0)
; #define G_WAIT_V(n) asm volatile("s_waitcnt vmcnt(" #n ")" ::: "memory")
; #define G_WAIT_L(n) asm volatile("s_waitcnt lgkmcnt(" #n ")" ::: "memory")
; #define G_BAR __builtin_amdgcn_s_barrier()
; #define G_SCHED __builtin_amdgcn_sched_barrier(0)
; template <class J>
; DI void gemm_phase(LAS unsigned char* lds, const J& job) {
;     ...
;       G_BAR; G_WAIT_L(0); G_MMA(1, 0, At, B0); G_BAR; G_SCHED;
;       G_STAGE(G_SB(1, 1), b3 + hstepB, voffB);
;       G_WAIT_V(6); G_BAR; G_MMA(1, 1, At, B1); G_BAR;
	s_waitcnt lgkmcnt(0)
	v_mfma_f32_16x16x32_bf16 v[60:63], v[84:87], v[154:157], v[60:63]
	v_mfma_f32_16x16x32_bf16 v[56:59], v[96:99], v[154:157], v[56:59]
	v_mfma_f32_16x16x32_bf16 v[44:47], v[84:87], v[162:165], v[44:47]
	v_mfma_f32_16x16x32_bf16 v[40:43], v[96:99], v[162:165], v[40:43]
	v_mfma_f32_16x16x32_bf16 v[28:31], v[84:87], v[170:173], v[28:31]
	v_mfma_f32_16x16x32_bf16 v[24:27], v[96:99], v[170:173], v[24:27]
	v_mfma_f32_16x16x32_bf16 v[12:15], v[84:87], v[178:181], v[12:15]
	v_mfma_f32_16x16x32_bf16 v[8:11], v[96:99], v[178:181], v[8:11]
	v_mfma_f32_16x16x32_bf16 v[60:63], v[88:91], v[158:161], v[60:63]
	v_mfma_f32_16x16x32_bf16 v[56:59], v[100:103], v[158:161], v[56:59]
	v_mfma_f32_16x16x32_bf16 v[44:47], v[88:91], v[166:169], v[44:47]
	v_mfma_f32_16x16x32_bf16 v[40:43], v[100:103], v[166:169], v[40:43]
	v_mfma_f32_16x16x32_bf16 v[28:31], v[88:91], v[174:177], v[28:31]
	v_mfma_f32_16x16x32_bf16 v[24:27], v[100:103], v[174:177], v[24:27]
	v_mfma_f32_16x16x32_bf16 v[12:15], v[88:91], v[182:185], v[12:15]
	v_mfma_f32_16x16x32_bf16 v[8:11], v[100:103], v[182:185], v[8:11]
	s_barrier
	s_add_u32 s0, s70, 0x1000000
	s_addc_u32 s1, s71, 0
	s_add_i32 s2, s38, s78
	v_lshl_add_u64 v[84:85], s[0:1], 0, v[146:147]
	s_mov_b32 m0, s2
	s_nop 0
	global_load_lds_dwordx4 v[84:85], off
	v_lshl_add_u64 v[84:85], s[0:1], 0, v[152:153]
	s_add_i32 m0, s2, 0x2000
	s_nop 0
	global_load_lds_dwordx4 v[84:85], off
	s_waitcnt vmcnt(6)
	s_barrier
	v_mfma_f32_16x16x32_bf16 v[52:55], v[186:189], v[154:157], v[52:55]
	v_mfma_f32_16x16x32_bf16 v[48:51], v[194:197], v[154:157], v[48:51]
	v_mfma_f32_16x16x32_bf16 v[36:39], v[186:189], v[162:165], v[36:39]
	v_mfma_f32_16x16x32_bf16 v[32:35], v[194:197], v[162:165], v[32:35]
	v_mfma_f32_16x16x32_bf16 v[20:23], v[186:189], v[170:173], v[20:23]
	v_mfma_f32_16x16x32_bf16 v[16:19], v[194:197], v[170:173], v[16:19]
	v_mfma_f32_16x16x32_bf16 v[4:7], v[186:189], v[178:181], v[4:7]
	v_mfma_f32_16x16x32_bf16 v[0:3], v[194:197], v[178:181], v[0:3]
	v_mfma_f32_16x16x32_bf16 v[52:55], v[190:193], v[158:161], v[52:55]
	v_mfma_f32_16x16x32_bf16 v[48:51], v[198:201], v[158:161], v[48:51]
	v_mfma_f32_16x16x32_bf16 v[36:39], v[190:193], v[166:169], v[36:39]
	v_mfma_f32_16x16x32_bf16 v[32:35], v[198:201], v[166:169], v[32:35]
	v_mfma_f32_16x16x32_bf16 v[20:23], v[190:193], v[174:177], v[20:23]
	v_mfma_f32_16x16x32_bf16 v[16:19], v[198:201], v[174:177], v[16:19]
	v_mfma_f32_16x16x32_bf16 v[4:7], v[190:193], v[182:185], v[4:7]
	v_mfma_f32_16x16x32_bf16 v[0:3], v[198:201], v[182:185], v[0:3]
	s_add_i32 s6, s6, 2
	s_addk_i32 s56, 0x100
	s_addk_i32 s7, 0x100
	s_cmp_gt_u32 s6, 29
	s_barrier
	s_cbranch_scc0 .LBB0_74
;   DI void epi(const Acc& acc, const Unit& u, int wr, int wc, int fr, int fq) const {
;     const int cc = u.pn * 64 + 16 * wc + 4 * fq;
;     u32x2 zz[2][4][4];
; #pragma unroll
;     for (int ai = 0; ai < 2; ++ai)
; #pragma unroll
;       for (int m = 0; m < 4; ++m) {
;         const u16* zr = Z + (size_t)(u.pm * 256 + ai * HALF + wr * 64 + m * 16 + fr) * NGATE + cc;
; #pragma unroll
;         for (int br = 0; br < 4; ++br) zz[ai][m][br] = *(const u32x2*)(zr + br * 2048);
;       }
;     f32x4 bg[4];
; #pragma unroll
;     for (int br = 0; br < 4; ++br) bg[br] = *(const f32x4*)(bgate + br * 2048 + cc);
	v_mov_b32_e32 v84, v247
	v_mov_b32_e32 v85, v246
	s_lshl_b32 s0, s44, 6
	s_or_b32 s0, s0, s96
	v_lshl_add_u32 v84, v84, 2, s0
	s_lshl_b32 s0, s64, 8
	s_add_i32 s0, s0, s37
	v_add_u32_e32 v224, s0, v85
	v_ashrrev_i32_e32 v85, 31, v84
	v_lshlrev_b64 v[154:155], 1, v[84:85]
	v_ashrrev_i32_e32 v225, 31, v224
	v_lshl_add_u64 v[86:87], s[26:27], 0, v[154:155]
	v_lshlrev_b64 v[88:89], 14, v[224:225]
	v_lshl_add_u64 v[88:89], v[86:87], 0, v[88:89]
	v_add_co_u32_e32 v90, vcc, s82, v88
	v_add_u32_e32 v212, 16, v224
	s_nop 0
	v_addc_co_u32_e32 v91, vcc, 0, v89, vcc
	v_ashrrev_i32_e32 v213, 31, v212
	v_add_co_u32_e32 v96, vcc, s92, v88
	v_lshlrev_b64 v[98:99], 14, v[212:213]
	s_nop 0
	v_addc_co_u32_e32 v97, vcc, 0, v89, vcc
	v_lshl_add_u64 v[98:99], v[86:87], 0, v[98:99]
	v_add_co_u32_e32 v100, vcc, s82, v98
	v_add_u32_e32 v202, 32, v224
	s_nop 0
	v_addc_co_u32_e32 v101, vcc, 0, v99, vcc
	global_load_dwordx2 v[230:231], v[90:91], off offset:-4096
	global_load_dwordx2 v[226:227], v[90:91], off
	global_load_dwordx2 v[220:221], v[100:101], off offset:-4096
	global_load_dwordx2 v[214:215], v[100:101], off
	v_add_co_u32_e32 v90, vcc, s92, v98
	v_ashrrev_i32_e32 v203, 31, v202
	s_nop 0
	v_addc_co_u32_e32 v91, vcc, 0, v99, vcc
	global_load_dwordx2 v[232:233], v[88:89], off
	global_load_dwordx2 v[228:229], v[96:97], off
	global_load_dwordx2 v[222:223], v[98:99], off
	global_load_dwordx2 v[216:217], v[90:91], off
	v_lshlrev_b64 v[88:89], 14, v[202:203]
	v_lshl_add_u64 v[88:89], v[86:87], 0, v[88:89]
	v_add_co_u32_e32 v90, vcc, s82, v88
	v_add_u32_e32 v190, 48, v224
	s_nop 0
	v_addc_co_u32_e32 v91, vcc, 0, v89, vcc
	v_ashrrev_i32_e32 v191, 31, v190
	v_add_co_u32_e32 v96, vcc, s92, v88
	v_lshlrev_b64 v[98:99], 14, v[190:191]
	s_nop 0
	v_addc_co_u32_e32 v97, vcc, 0, v89, vcc
	v_lshl_add_u64 v[98:99], v[86:87], 0, v[98:99]
	v_add_co_u32_e32 v100, vcc, s82, v98
	v_add_u32_e32 v184, 0x80, v224
	s_nop 0
	v_addc_co_u32_e32 v101, vcc, 0, v99, vcc
	global_load_dwordx2 v[210:211], v[90:91], off offset:-4096
	global_load_dwordx2 v[206:207], v[90:91], off
	global_load_dwordx2 v[200:201], v[100:101], off offset:-4096
	global_load_dwordx2 v[192:193], v[100:101], off
	v_add_co_u32_e32 v90, vcc, s92, v98
	v_lshl_add_u64 v[84:85], v[84:85], 2, s[12:13]
	v_ashrrev_i32_e32 v185, 31, v184
	v_addc_co_u32_e32 v91, vcc, 0, v99, vcc
	global_load_dwordx4 v[100:103], v[84:85], off
	global_load_dwordx2 v[218:219], v[88:89], off
	global_load_dwordx2 v[208:209], v[96:97], off
	global_load_dwordx2 v[204:205], v[98:99], off
	global_load_dwordx2 v[198:199], v[90:91], off
	v_lshlrev_b64 v[88:89], 14, v[184:185]
	v_lshl_add_u64 v[88:89], v[86:87], 0, v[88:89]
	v_add_co_u32_e32 v90, vcc, s82, v88
	v_add_u32_e32 v174, 0x90, v224
	s_nop 0
	v_addc_co_u32_e32 v91, vcc, 0, v89, vcc
	v_add_co_u32_e32 v156, vcc, s92, v88
	v_ashrrev_i32_e32 v175, 31, v174
	s_nop 0
	v_addc_co_u32_e32 v157, vcc, 0, v89, vcc
	v_add_co_u32_e32 v96, vcc, s82, v84
	v_lshlrev_b64 v[158:159], 14, v[174:175]
	s_nop 0
	v_addc_co_u32_e32 v97, vcc, 0, v85, vcc
	global_load_dwordx4 v[96:99], v[96:97], off
	v_lshl_add_u64 v[158:159], v[86:87], 0, v[158:159]
	v_add_co_u32_e32 v160, vcc, s82, v158
	v_add_u32_e32 v164, 0xa0, v224
	s_nop 0
	v_addc_co_u32_e32 v161, vcc, 0, v159, vcc
	global_load_dwordx2 v[194:195], v[90:91], off offset:-4096
	global_load_dwordx2 v[186:187], v[90:91], off
	global_load_dwordx2 v[180:181], v[160:161], off offset:-4096
	global_load_dwordx2 v[176:177], v[160:161], off
	v_add_co_u32_e32 v90, vcc, s92, v158
	v_ashrrev_i32_e32 v165, 31, v164
	s_nop 0
	v_addc_co_u32_e32 v91, vcc, 0, v159, vcc
	global_load_dwordx2 v[196:197], v[88:89], off
	global_load_dwordx2 v[188:189], v[156:157], off
	global_load_dwordx2 v[182:183], v[158:159], off
	global_load_dwordx2 v[178:179], v[90:91], off
	v_lshlrev_b64 v[88:89], 14, v[164:165]
	v_lshl_add_u64 v[162:163], v[86:87], 0, v[88:89]
	v_add_co_u32_e32 v158, vcc, s82, v162
	v_add_u32_e32 v156, 0xb0, v224
	s_nop 0
	v_addc_co_u32_e32 v159, vcc, 0, v163, vcc
	v_add_co_u32_e32 v168, vcc, s92, v162
	v_ashrrev_i32_e32 v157, 31, v156
	s_nop 0
	v_addc_co_u32_e32 v169, vcc, 0, v163, vcc
	v_add_co_u32_e32 v88, vcc, s54, v84
	v_lshlrev_b64 v[160:161], 14, v[156:157]
	s_nop 0
	v_addc_co_u32_e32 v89, vcc, 0, v85, vcc
	global_load_dwordx4 v[88:91], v[88:89], off
	v_lshl_add_u64 v[250:251], v[86:87], 0, v[160:161]
	v_add_co_u32_e32 v86, vcc, s82, v250
	s_mov_b32 s44, s20
	s_nop 0
	v_addc_co_u32_e32 v87, vcc, 0, v251, vcc
	v_add_co_u32_e32 v84, vcc, s55, v84
	global_load_dwordx2 v[170:171], v[158:159], off offset:-4096
	global_load_dwordx2 v[166:167], v[158:159], off
	global_load_dwordx2 v[160:161], v[86:87], off offset:-4096
	s_nop 0
	global_load_dwordx2 v[158:159], v[86:87], off
	v_addc_co_u32_e32 v85, vcc, 0, v85, vcc
	global_load_dwordx4 v[84:87], v[84:85], off
	v_add_co_u32_e32 v252, vcc, s92, v250
	s_mov_b32 s64, s18
	s_nop 0
	v_addc_co_u32_e32 v253, vcc, 0, v251, vcc
	s_and_b64 vcc, exec, s[8:9]
	s_mov_b64 s[66:67], s[62:63]
	s_mov_b64 s[68:69], s[22:23]
	v_readlane_b32 s0, v255, 23
	s_cmpk_gt_u32 s0, 0xff
	s_cbranch_scc1 .Lds_gate_x
	s_barrier

; #define G_STAGE(bufoff, gbase, voff) do { _Pragma("unroll") for (int _i = 0; _i < 2; ++_i) \
;         __builtin_amdgcn_global_load_lds((const unsigned*)((const char*)(gbase) + (voff)[_i]), (LAS unsigned*)(lds + (bufoff) + ldsw + _i * 8192), 16, 0, 0); } while (0)
; #define G_LDA(dst, b, h) do { _Pragma("unroll") for (int m = 0; m < 4; ++m) _Pragma("unroll") for (int k = 0; k < 2; ++k) dst[m][k] = *(const LAS bf16x8*)(lds + G_SA(b, h) + aoff + m * 2048 + k * 1024); } while (0)
; #define G_LDB(dst, b, h) do { _Pragma("unroll") for (int n = 0; n < 2; ++n) _Pragma("unroll") for (int k = 0; k < 2; ++k) dst[n][k] = *(const LAS bf16x8*)(lds + G_SB(b, h) + boff + n * 2048 + k * 1024); } while (0)
; #define G_MMA(ai, bj, At, Bt) do { __builtin_amdgcn_s_setprio(1); _Pragma("unroll") for (int m = 0; m < 4; ++m) _Pragma("unroll") for (int n = 0; n < 2; ++n) _Pragma("unroll") for (int k = 0; k < 2; ++k) \
;         acc[ai][bj][m][n] = __builtin_amdgcn_mfma_f32_16x16x32_bf16(Bt[n][k], At[m][k], acc[ai][bj][m][n], 0, 0, 0); __builtin_amdgcn_s_setprio(0); } while (0)
; #define G_WAIT_L(n) asm volatile("s_waitcnt lgkmcnt(" #n ")" ::: "memory")
; #define G_BAR __builtin_amdgcn_s_barrier()
; #define G_SCHED __builtin_amdgcn_sched_barrier(0)
; template <class J>
; DI void gemm_phase(LAS unsigned char* lds, const J& job) {
;     ...
;     for (int t = 0; t < nt; t += 2) {
;       const bool last = (t == nt - 2);
;       const char* a1 = cA + G_KT(t + 1);
;       const char* a2 = last ? nA + G_KT(0) : cA + G_KT(t + 2); const char* b2 = last ? nB + G_KT(0) : cB + G_KT(t + 2);
;       const char* a3 = last ? nA + G_KT(1) : cA + G_KT(t + 3); const char* b3 = last ? nB + G_KT(1) : cB + G_KT(t + 3);
;       G_LDB(B0, 0, 0); G_SCHED; G_LDA(At, 0, 0); G_STAGE(G_SA(1, 1), a1 + hstepA, voffA);
;       G_WAIT_L(8); G_BAR; G_WAIT_L(0); G_MMA(0, 0, At, B0); G_BAR; G_SCHED;
;       G_LDB(B1, 0, 1); G_STAGE(G_SB(0, 0), b2, voffB);
;       G_BAR; G_WAIT_L(0); G_MMA(0, 1, At, B1); G_BAR;
;       G_LDA(At, 0, 1); G_STAGE(G_SA(0, 0), a2, voffA);
;       G_BAR; G_WAIT_L(0); G_MMA(1, 0, At, B0); G_BAR; G_SCHED;
.LBB0_104:
	s_add_i32 s1, s56, 0xffffff80
	s_and_b32 s0, s7, 0x380
	s_and_b32 s1, s1, 0x380
	s_add_u32 s57, s64, s1
	s_addc_u32 s66, s65, 0
	s_add_u32 s1, s62, s1
	s_addc_u32 s67, s63, 0
	s_and_b32 s68, s56, 0x380
	s_add_u32 s80, s64, s68
	s_addc_u32 s69, s65, 0
	s_add_u32 s97, s62, s68
	s_addc_u32 vcc_lo, s63, 0
	s_cmp_eq_u32 s6, 4
	s_cselect_b32 s71, s83, s66
	s_cselect_b32 s70, s47, s57
	s_cselect_b32 s73, s87, s67
	s_cselect_b32 s72, s86, s1
	s_cselect_b32 s69, s94, s69
	s_cselect_b32 s68, s33, s80
	s_cselect_b32 s67, s5, vcc_lo
	s_cselect_b32 s66, s96, s97
	s_add_i32 s1, s84, 0x100
	v_add_u32_e32 v134, s1, v138
	ds_read_b128 v[140:143], v134
	ds_read_b128 v[148:151], v134 offset:1024
	ds_read_b128 v[152:155], v134 offset:2048
	ds_read_b128 v[156:159], v134 offset:3072
	s_add_u32 vcc_lo, s9, s0
	s_addc_u32 vcc_hi, s17, 0
	v_lshl_add_u64 v[134:135], vcc, 0, v[132:133]
	s_add_i32 m0, s25, 0xc000
	ds_read_b128 v[160:163], v139
	ds_read_b128 v[164:167], v139 offset:1024
	ds_read_b128 v[168:171], v139 offset:2048
	ds_read_b128 v[172:175], v139 offset:3072
	ds_read_b128 v[176:179], v139 offset:4096
	ds_read_b128 v[180:183], v139 offset:5120
	ds_read_b128 v[184:187], v139 offset:6144
	ds_read_b128 v[188:191], v139 offset:7168
	global_load_lds_dwordx4 v[134:135], off
	v_lshl_add_u64 v[134:135], vcc, 0, v[130:131]
	s_add_i32 m0, s25, 0xe000
	s_nop 0
	global_load_lds_dwordx4 v[134:135], off
	s_waitcnt lgkmcnt(8)
	s_barrier
	s_waitcnt lgkmcnt(7)
	v_mfma_f32_16x16x32_bf16 v[124:127], v[140:143], v[160:163], v[124:127]
	v_mfma_f32_16x16x32_bf16 v[120:123], v[152:155], v[160:163], v[120:123]
	s_waitcnt lgkmcnt(5)
	v_mfma_f32_16x16x32_bf16 v[116:119], v[140:143], v[168:171], v[116:119]
	v_mfma_f32_16x16x32_bf16 v[108:111], v[152:155], v[168:171], v[108:111]
	s_waitcnt lgkmcnt(3)
	v_mfma_f32_16x16x32_bf16 v[100:103], v[140:143], v[176:179], v[100:103]
	v_mfma_f32_16x16x32_bf16 v[92:95], v[152:155], v[176:179], v[92:95]
	s_waitcnt lgkmcnt(1)
	v_mfma_f32_16x16x32_bf16 v[84:87], v[140:143], v[184:187], v[84:87]
	v_mfma_f32_16x16x32_bf16 v[76:79], v[152:155], v[184:187], v[76:79]
	v_mfma_f32_16x16x32_bf16 v[124:127], v[148:151], v[164:167], v[124:127]
	v_mfma_f32_16x16x32_bf16 v[120:123], v[156:159], v[164:167], v[120:123]
	v_mfma_f32_16x16x32_bf16 v[116:119], v[148:151], v[172:175], v[116:119]
	v_mfma_f32_16x16x32_bf16 v[108:111], v[156:159], v[172:175], v[108:111]
	v_mfma_f32_16x16x32_bf16 v[100:103], v[148:151], v[180:183], v[100:103]
	v_mfma_f32_16x16x32_bf16 v[92:95], v[156:159], v[180:183], v[92:95]
	s_waitcnt lgkmcnt(0)
	v_mfma_f32_16x16x32_bf16 v[84:87], v[148:151], v[188:191], v[84:87]
	v_mfma_f32_16x16x32_bf16 v[76:79], v[156:159], v[188:191], v[76:79]
	s_barrier
	s_add_i32 s0, s85, 0x100
	v_add_u32_e32 v134, s0, v138
	s_add_i32 s1, s1, s24
	ds_read_b128 v[192:195], v134
	ds_read_b128 v[196:199], v134 offset:1024
	ds_read_b128 v[200:203], v134 offset:2048
	ds_read_b128 v[204:207], v134 offset:3072
	v_lshl_add_u64 v[134:135], s[72:73], 0, v[146:147]
	s_mov_b32 m0, s1
	s_nop 0
	global_load_lds_dwordx4 v[134:135], off
	v_lshl_add_u64 v[134:135], s[72:73], 0, v[128:129]
	s_add_i32 m0, s1, 0x2000
	s_nop 0
	global_load_lds_dwordx4 v[134:135], off
	s_barrier
	s_waitcnt lgkmcnt(0)
	v_mfma_f32_16x16x32_bf16 v[112:115], v[192:195], v[160:163], v[112:115]
	v_mfma_f32_16x16x32_bf16 v[104:107], v[200:203], v[160:163], v[104:107]
	v_mfma_f32_16x16x32_bf16 v[96:99], v[192:195], v[168:171], v[96:99]
	v_mfma_f32_16x16x32_bf16 v[88:91], v[200:203], v[168:171], v[88:91]
	v_mfma_f32_16x16x32_bf16 v[80:83], v[192:195], v[176:179], v[80:83]
	v_mfma_f32_16x16x32_bf16 v[72:75], v[200:203], v[176:179], v[72:75]
	v_mfma_f32_16x16x32_bf16 v[68:71], v[192:195], v[184:187], v[68:71]
	v_mfma_f32_16x16x32_bf16 v[64:67], v[200:203], v[184:187], v[64:67]
	v_mfma_f32_16x16x32_bf16 v[112:115], v[196:199], v[164:167], v[112:115]
	v_mfma_f32_16x16x32_bf16 v[104:107], v[204:207], v[164:167], v[104:107]
	v_mfma_f32_16x16x32_bf16 v[96:99], v[196:199], v[172:175], v[96:99]
	v_mfma_f32_16x16x32_bf16 v[88:91], v[204:207], v[172:175], v[88:91]
	v_mfma_f32_16x16x32_bf16 v[80:83], v[196:199], v[180:183], v[80:83]
	v_mfma_f32_16x16x32_bf16 v[72:75], v[204:207], v[180:183], v[72:75]
	v_mfma_f32_16x16x32_bf16 v[68:71], v[196:199], v[188:191], v[68:71]
	v_mfma_f32_16x16x32_bf16 v[64:67], v[204:207], v[188:191], v[64:67]
	s_mov_b32 m0, s25
	v_lshl_add_u64 v[134:135], s[70:71], 0, v[132:133]
	s_barrier
	ds_read_b128 v[160:163], v139 offset:16384
	ds_read_b128 v[164:167], v139 offset:17408
	ds_read_b128 v[168:171], v139 offset:18432
	ds_read_b128 v[172:175], v139 offset:19456
	ds_read_b128 v[176:179], v139 offset:20480
	ds_read_b128 v[180:183], v139 offset:21504
	ds_read_b128 v[184:187], v139 offset:22528
	ds_read_b128 v[188:191], v139 offset:23552
	global_load_lds_dwordx4 v[134:135], off
	v_lshl_add_u64 v[134:135], s[70:71], 0, v[130:131]
	s_mov_b32 m0, s36
	s_nop 0
	global_load_lds_dwordx4 v[134:135], off
	s_barrier
	s_waitcnt lgkmcnt(0)
	v_mfma_f32_16x16x32_bf16 v[60:63], v[140:143], v[160:163], v[60:63]
	v_mfma_f32_16x16x32_bf16 v[56:59], v[152:155], v[160:163], v[56:59]
	v_mfma_f32_16x16x32_bf16 v[52:55], v[140:143], v[168:171], v[52:55]
	v_mfma_f32_16x16x32_bf16 v[44:47], v[152:155], v[168:171], v[44:47]
	v_mfma_f32_16x16x32_bf16 v[36:39], v[140:143], v[176:179], v[36:39]
	v_mfma_f32_16x16x32_bf16 v[28:31], v[152:155], v[176:179], v[28:31]
	v_mfma_f32_16x16x32_bf16 v[20:23], v[140:143], v[184:187], v[20:23]
	v_mfma_f32_16x16x32_bf16 v[12:15], v[152:155], v[184:187], v[12:15]
	v_mfma_f32_16x16x32_bf16 v[60:63], v[148:151], v[164:167], v[60:63]
	v_mfma_f32_16x16x32_bf16 v[56:59], v[156:159], v[164:167], v[56:59]
	v_mfma_f32_16x16x32_bf16 v[52:55], v[148:151], v[172:175], v[52:55]
	v_mfma_f32_16x16x32_bf16 v[44:47], v[156:159], v[172:175], v[44:47]
	v_mfma_f32_16x16x32_bf16 v[36:39], v[148:151], v[180:183], v[36:39]
	v_mfma_f32_16x16x32_bf16 v[28:31], v[156:159], v[180:183], v[28:31]
	v_mfma_f32_16x16x32_bf16 v[20:23], v[148:151], v[188:191], v[20:23]
	v_mfma_f32_16x16x32_bf16 v[12:15], v[156:159], v[188:191], v[12:15]
	s_barrier
; #define G_STAGE(bufoff, gbase, voff) do { _Pragma("unroll") for (int _i = 0; _i < 2; ++_i) \
;         __builtin_amdgcn_global_load_lds((const unsigned*)((const char*)(gbase) + (voff)[_i]), (LAS unsigned*)(lds + (bufoff) + ldsw + _i * 8192), 16, 0, 0); } while (0)
; #define G_LDA(dst, b, h) do { _Pragma("unroll") for (int m = 0; m < 4; ++m) _Pragma("unroll") for (int k = 0; k < 2; ++k) dst[m][k] = *(const LAS bf16x8*)(lds + G_SA(b, h) + aoff + m * 2048 + k * 1024); } while (0)
; #define G_LDB(dst, b, h) do { _Pragma("unroll") for (int n = 0; n < 2; ++n) _Pragma("unroll") for (int k = 0; k < 2; ++k) dst[n][k] = *(const LAS bf16x8*)(lds + G_SB(b, h) + boff + n * 2048 + k * 1024); } while (0)
; #define G_MMA(ai, bj, At, Bt) do { __builtin_amdgcn_s_setprio(1); _Pragma("unroll") for (int m = 0; m < 4; ++m) _Pragma("unroll") for (int n = 0; n < 2; ++n) _Pragma("unroll") for (int k = 0; k < 2; ++k) \
;         acc[ai][bj][m][n] = __builtin_amdgcn_mfma_f32_16x16x32_bf16(Bt[n][k], At[m][k], acc[ai][bj][m][n], 0, 0, 0); __builtin_amdgcn_s_setprio(0); } while (0)
; #define G_WAIT_V(n) asm volatile("s_waitcnt vmcnt(" #n ")" ::: "memory")
; #define G_WAIT_L(n) asm volatile("s_waitcnt lgkmcnt(" #n ")" ::: "memory")
; #define G_BAR __builtin_amdgcn_s_barrier()
; #define G_SCHED __builtin_amdgcn_sched_barrier(0)
; template <class J>
; DI void gemm_phase(LAS unsigned char* lds, const J& job) {
;     ...
;       G_STAGE(G_SB(0, 1), b2 + hstepB, voffB);
;       G_WAIT_V(6); G_BAR; G_MMA(1, 1, At, B1); G_BAR;
;       G_LDB(B0, 1, 0); G_SCHED; G_LDA(At, 1, 0); G_STAGE(G_SA(0, 1), a2 + hstepA, voffA);
;       G_WAIT_L(8); G_BAR; G_WAIT_L(0); G_MMA(0, 0, At, B0); G_BAR; G_SCHED;
;       G_LDB(B1, 1, 1); G_STAGE(G_SB(1, 0), b3, voffB);
;       G_BAR; G_WAIT_L(0); G_MMA(0, 1, At, B1); G_BAR;
;       G_LDA(At, 1, 1); G_STAGE(G_SA(1, 0), a3, voffA);
	s_add_u32 s72, s72, 0x20000
	s_addc_u32 s73, s73, 0
	s_add_i32 s0, s0, s24
	v_lshl_add_u64 v[134:135], s[72:73], 0, v[146:147]
	s_mov_b32 m0, s0
	s_nop 0
	global_load_lds_dwordx4 v[134:135], off
	v_lshl_add_u64 v[134:135], s[72:73], 0, v[128:129]
	s_add_i32 m0, s0, 0x2000
	s_nop 0
	global_load_lds_dwordx4 v[134:135], off
	s_waitcnt vmcnt(6)
	s_barrier
	v_mfma_f32_16x16x32_bf16 v[48:51], v[192:195], v[160:163], v[48:51]
	v_mfma_f32_16x16x32_bf16 v[40:43], v[200:203], v[160:163], v[40:43]
	v_mfma_f32_16x16x32_bf16 v[32:35], v[192:195], v[168:171], v[32:35]
	v_mfma_f32_16x16x32_bf16 v[24:27], v[200:203], v[168:171], v[24:27]
	v_mfma_f32_16x16x32_bf16 v[16:19], v[192:195], v[176:179], v[16:19]
	v_mfma_f32_16x16x32_bf16 v[8:11], v[200:203], v[176:179], v[8:11]
	v_mfma_f32_16x16x32_bf16 v[4:7], v[192:195], v[184:187], v[4:7]
	v_mfma_f32_16x16x32_bf16 v[0:3], v[200:203], v[184:187], v[0:3]
	v_mfma_f32_16x16x32_bf16 v[48:51], v[196:199], v[164:167], v[48:51]
	v_mfma_f32_16x16x32_bf16 v[40:43], v[204:207], v[164:167], v[40:43]
	v_mfma_f32_16x16x32_bf16 v[32:35], v[196:199], v[172:175], v[32:35]
	v_mfma_f32_16x16x32_bf16 v[24:27], v[204:207], v[172:175], v[24:27]
	v_mfma_f32_16x16x32_bf16 v[16:19], v[196:199], v[180:183], v[16:19]
	v_mfma_f32_16x16x32_bf16 v[8:11], v[204:207], v[180:183], v[8:11]
	v_mfma_f32_16x16x32_bf16 v[4:7], v[196:199], v[188:191], v[4:7]
	v_mfma_f32_16x16x32_bf16 v[0:3], v[204:207], v[188:191], v[0:3]
	s_add_i32 s0, s88, 0x100
	v_add_u32_e32 v134, s0, v138
	s_barrier
	ds_read_b128 v[140:143], v134
	ds_read_b128 v[148:151], v134 offset:1024
	ds_read_b128 v[152:155], v134 offset:2048
	ds_read_b128 v[156:159], v134 offset:3072
	s_add_u32 s70, s70, 0x80000
	s_addc_u32 s71, s71, 0
	s_mov_b32 m0, s37
	v_lshl_add_u64 v[134:135], s[70:71], 0, v[132:133]
	ds_read_b128 v[160:163], v139 offset:32768
	ds_read_b128 v[164:167], v139 offset:33792
	ds_read_b128 v[168:171], v139 offset:34816
	ds_read_b128 v[172:175], v139 offset:35840
	ds_read_b128 v[176:179], v139 offset:36864
	ds_read_b128 v[180:183], v139 offset:37888
	ds_read_b128 v[184:187], v139 offset:38912
	ds_read_b128 v[188:191], v139 offset:39936
	global_load_lds_dwordx4 v[134:135], off
	v_lshl_add_u64 v[134:135], s[70:71], 0, v[130:131]
	s_mov_b32 m0, s38
	s_nop 0
	global_load_lds_dwordx4 v[134:135], off
	s_waitcnt lgkmcnt(8)
	s_barrier
	s_waitcnt lgkmcnt(7)
	v_mfma_f32_16x16x32_bf16 v[124:127], v[140:143], v[160:163], v[124:127]
	v_mfma_f32_16x16x32_bf16 v[120:123], v[152:155], v[160:163], v[120:123]
	s_waitcnt lgkmcnt(5)
	v_mfma_f32_16x16x32_bf16 v[116:119], v[140:143], v[168:171], v[116:119]
	v_mfma_f32_16x16x32_bf16 v[108:111], v[152:155], v[168:171], v[108:111]
	s_waitcnt lgkmcnt(3)
	v_mfma_f32_16x16x32_bf16 v[100:103], v[140:143], v[176:179], v[100:103]
	v_mfma_f32_16x16x32_bf16 v[92:95], v[152:155], v[176:179], v[92:95]
	s_waitcnt lgkmcnt(1)
	v_mfma_f32_16x16x32_bf16 v[84:87], v[140:143], v[184:187], v[84:87]
	v_mfma_f32_16x16x32_bf16 v[76:79], v[152:155], v[184:187], v[76:79]
	v_mfma_f32_16x16x32_bf16 v[124:127], v[148:151], v[164:167], v[124:127]
	v_mfma_f32_16x16x32_bf16 v[120:123], v[156:159], v[164:167], v[120:123]
	v_mfma_f32_16x16x32_bf16 v[116:119], v[148:151], v[172:175], v[116:119]
	v_mfma_f32_16x16x32_bf16 v[108:111], v[156:159], v[172:175], v[108:111]
	v_mfma_f32_16x16x32_bf16 v[100:103], v[148:151], v[180:183], v[100:103]
	v_mfma_f32_16x16x32_bf16 v[92:95], v[156:159], v[180:183], v[92:95]
	s_waitcnt lgkmcnt(0)
	v_mfma_f32_16x16x32_bf16 v[84:87], v[148:151], v[188:191], v[84:87]
	v_mfma_f32_16x16x32_bf16 v[76:79], v[156:159], v[188:191], v[76:79]
	s_barrier
	s_add_i32 s1, s89, 0x100
	v_add_u32_e32 v134, s1, v138
	s_add_i32 s0, s0, s24
	ds_read_b128 v[192:195], v134
	ds_read_b128 v[196:199], v134 offset:1024
	ds_read_b128 v[200:203], v134 offset:2048
	ds_read_b128 v[204:207], v134 offset:3072
	v_lshl_add_u64 v[134:135], s[66:67], 0, v[146:147]
	s_mov_b32 m0, s0
	s_nop 0
	global_load_lds_dwordx4 v[134:135], off
	v_lshl_add_u64 v[134:135], s[66:67], 0, v[128:129]
	s_add_i32 m0, s0, 0x2000
	s_nop 0
	global_load_lds_dwordx4 v[134:135], off
	s_barrier
	s_waitcnt lgkmcnt(0)
	v_mfma_f32_16x16x32_bf16 v[112:115], v[192:195], v[160:163], v[112:115]
	v_mfma_f32_16x16x32_bf16 v[104:107], v[200:203], v[160:163], v[104:107]
	v_mfma_f32_16x16x32_bf16 v[96:99], v[192:195], v[168:171], v[96:99]
	v_mfma_f32_16x16x32_bf16 v[88:91], v[200:203], v[168:171], v[88:91]
	v_mfma_f32_16x16x32_bf16 v[80:83], v[192:195], v[176:179], v[80:83]
	v_mfma_f32_16x16x32_bf16 v[72:75], v[200:203], v[176:179], v[72:75]
	v_mfma_f32_16x16x32_bf16 v[68:71], v[192:195], v[184:187], v[68:71]
	v_mfma_f32_16x16x32_bf16 v[64:67], v[200:203], v[184:187], v[64:67]
	v_mfma_f32_16x16x32_bf16 v[112:115], v[196:199], v[164:167], v[112:115]
	v_mfma_f32_16x16x32_bf16 v[104:107], v[204:207], v[164:167], v[104:107]
	v_mfma_f32_16x16x32_bf16 v[96:99], v[196:199], v[172:175], v[96:99]
	v_mfma_f32_16x16x32_bf16 v[88:91], v[204:207], v[172:175], v[88:91]
	v_mfma_f32_16x16x32_bf16 v[80:83], v[196:199], v[180:183], v[80:83]
	v_mfma_f32_16x16x32_bf16 v[72:75], v[204:207], v[180:183], v[72:75]
	v_mfma_f32_16x16x32_bf16 v[68:71], v[196:199], v[188:191], v[68:71]
	v_mfma_f32_16x16x32_bf16 v[64:67], v[204:207], v[188:191], v[64:67]
	s_mov_b32 m0, s75
	v_lshl_add_u64 v[134:135], s[68:69], 0, v[132:133]
	s_barrier
	ds_read_b128 v[160:163], v139 offset:49152
	ds_read_b128 v[164:167], v139 offset:50176
	ds_read_b128 v[168:171], v139 offset:51200
	ds_read_b128 v[172:175], v139 offset:52224
	ds_read_b128 v[176:179], v139 offset:53248
	ds_read_b128 v[180:183], v139 offset:54272
	ds_read_b128 v[184:187], v139 offset:55296
	ds_read_b128 v[188:191], v139 offset:56320
	global_load_lds_dwordx4 v[134:135], off
	v_lshl_add_u64 v[134:135], s[68:69], 0, v[130:131]
	s_mov_b32 m0, s76
	s_nop 0
	global_load_lds_dwordx4 v[134:135], off
	s_barrier
; #define G_STAGE(bufoff, gbase, voff) do { _Pragma("unroll") for (int _i = 0; _i < 2; ++_i) \
;         __builtin_amdgcn_global_load_lds((const unsigned*)((const char*)(gbase) + (voff)[_i]), (LAS unsigned*)(lds + (bufoff) + ldsw + _i * 8192), 16, 0, 0); } while (0)
; #define G_MMA(ai, bj, At, Bt) do { __builtin_amdgcn_s_setprio(1); _Pragma("unroll") for (int m = 0; m < 4; ++m) _Pragma("unroll") for (int n = 0; n < 2; ++n) _Pragma("unroll") for (int k = 0; k < 2; ++k) \
;         acc[ai][bj][m][n] = __builtin_amdgcn_mfma_f32_16x16x32_bf16(Bt[n][k], At[m][k], acc[ai][bj][m][n], 0, 0, 0); __builtin_amdgcn_s_setprio(0); } while (0)
; #define G_WAIT_V(n) asm volatile("s_waitcnt vmcnt(" #n ")" ::: "memory")
; #define G_WAIT_L(n) asm volatile("s_waitcnt lgkmcnt(" #n ")" ::: "memory")
; #define G_BAR __builtin_amdgcn_s_barrier()
; #define G_SCHED __builtin_amdgcn_sched_barrier(0)
; template <class J>
; DI void gemm_phase(LAS unsigned char* lds, const J& job) {
;     ...
;       G_BAR; G_WAIT_L(0); G_MMA(1, 0, At, B0); G_BAR; G_SCHED;
;       G_STAGE(G_SB(1, 1), b3 + hstepB, voffB);
;       G_WAIT_V(6); G_BAR; G_MMA(1, 1, At, B1); G_BAR;
	s_waitcnt lgkmcnt(0)
	v_mfma_f32_16x16x32_bf16 v[60:63], v[140:143], v[160:163], v[60:63]
	v_mfma_f32_16x16x32_bf16 v[56:59], v[152:155], v[160:163], v[56:59]
	v_mfma_f32_16x16x32_bf16 v[52:55], v[140:143], v[168:171], v[52:55]
	v_mfma_f32_16x16x32_bf16 v[44:47], v[152:155], v[168:171], v[44:47]
	v_mfma_f32_16x16x32_bf16 v[36:39], v[140:143], v[176:179], v[36:39]
	v_mfma_f32_16x16x32_bf16 v[28:31], v[152:155], v[176:179], v[28:31]
	v_mfma_f32_16x16x32_bf16 v[20:23], v[140:143], v[184:187], v[20:23]
	v_mfma_f32_16x16x32_bf16 v[12:15], v[152:155], v[184:187], v[12:15]
	v_mfma_f32_16x16x32_bf16 v[60:63], v[148:151], v[164:167], v[60:63]
	v_mfma_f32_16x16x32_bf16 v[56:59], v[156:159], v[164:167], v[56:59]
	v_mfma_f32_16x16x32_bf16 v[52:55], v[148:151], v[172:175], v[52:55]
	v_mfma_f32_16x16x32_bf16 v[44:47], v[156:159], v[172:175], v[44:47]
	v_mfma_f32_16x16x32_bf16 v[36:39], v[148:151], v[180:183], v[36:39]
	v_mfma_f32_16x16x32_bf16 v[28:31], v[156:159], v[180:183], v[28:31]
	v_mfma_f32_16x16x32_bf16 v[20:23], v[148:151], v[188:191], v[20:23]
	v_mfma_f32_16x16x32_bf16 v[12:15], v[156:159], v[188:191], v[12:15]
	s_barrier
	s_add_u32 s66, s66, 0x20000
	s_addc_u32 s67, s67, 0
	s_add_i32 s0, s1, s24
	v_lshl_add_u64 v[134:135], s[66:67], 0, v[146:147]
	s_mov_b32 m0, s0
	s_nop 0
	global_load_lds_dwordx4 v[134:135], off
	v_lshl_add_u64 v[134:135], s[66:67], 0, v[128:129]
	s_add_i32 m0, s0, 0x2000
	s_nop 0
	global_load_lds_dwordx4 v[134:135], off
	s_waitcnt vmcnt(6)
	s_barrier
	v_mfma_f32_16x16x32_bf16 v[48:51], v[192:195], v[160:163], v[48:51]
	v_mfma_f32_16x16x32_bf16 v[40:43], v[200:203], v[160:163], v[40:43]
	v_mfma_f32_16x16x32_bf16 v[32:35], v[192:195], v[168:171], v[32:35]
	v_mfma_f32_16x16x32_bf16 v[24:27], v[200:203], v[168:171], v[24:27]
	v_mfma_f32_16x16x32_bf16 v[16:19], v[192:195], v[176:179], v[16:19]
	v_mfma_f32_16x16x32_bf16 v[8:11], v[200:203], v[176:179], v[8:11]
	v_mfma_f32_16x16x32_bf16 v[4:7], v[192:195], v[184:187], v[4:7]
	v_mfma_f32_16x16x32_bf16 v[0:3], v[200:203], v[184:187], v[0:3]
	v_mfma_f32_16x16x32_bf16 v[48:51], v[196:199], v[164:167], v[48:51]
	v_mfma_f32_16x16x32_bf16 v[40:43], v[204:207], v[164:167], v[40:43]
	v_mfma_f32_16x16x32_bf16 v[32:35], v[196:199], v[172:175], v[32:35]
	v_mfma_f32_16x16x32_bf16 v[24:27], v[204:207], v[172:175], v[24:27]
	v_mfma_f32_16x16x32_bf16 v[16:19], v[196:199], v[180:183], v[16:19]
	v_mfma_f32_16x16x32_bf16 v[8:11], v[204:207], v[180:183], v[8:11]
	v_mfma_f32_16x16x32_bf16 v[4:7], v[196:199], v[188:191], v[4:7]
	v_mfma_f32_16x16x32_bf16 v[0:3], v[204:207], v[188:191], v[0:3]
	s_add_i32 s6, s6, 2
	s_addk_i32 s56, 0x100
	s_addk_i32 s7, 0x100
	s_cmp_gt_u32 s6, 5
	s_barrier
	s_cbranch_scc0 .LBB0_104
; DI unsigned pk2(float lo, float hi) { unsigned r; asm("v_cvt_pk_bf16_f32 %0, %1, %2" : "=v"(r) : "v"(lo), "v"(hi)); return r; }
;   DI void epi(const Acc& acc, const Unit& u, int wr, int wc, int fr, int fq) const {
; #pragma unroll
;     for (int ai = 0; ai < 2; ++ai)
; #pragma unroll
;       for (int m = 0; m < 4; ++m) {
;         const int row = u.pm * 256 + ai * HALF + wr * 64 + m * 16 + fr;
; #pragma unroll
;         for (int bj = 0; bj < 2; ++bj) {
;           const int col = u.pn * 256 + bj * HALF + wc * 32 + 8 * fq;
;           const f32x4 v0 = acc[ai][bj][m][0], v1 = acc[ai][bj][m][1];
;           u32x4 o; o.x = pk2(v0.x, v0.y); o.y = pk2(v0.z, v0.w); o.z = pk2(v1.x, v1.y); o.w = pk2(v1.z, v1.w);
;           *(u32x4*)(Z + (size_t)row * NGATE + col) = o;
;         }
;       }
;   }
	v_mov_b32_e32 v135, v137
	v_mov_b32_e32 v134, v136
	s_lshl_b32 s0, s22, 8
	s_add_i32 s0, s0, s44
	v_add_u32_e32 v134, s0, v134
	s_lshl_b32 s0, s46, 8
	s_or_b32 s0, s0, s45
	v_cvt_pk_bf16_f32 v68, v68, v69
	v_cvt_pk_bf16_f32 v69, v70, v71
	v_cvt_pk_bf16_f32 v70, v64, v65
	v_add_u32_e32 v64, 0x80, v134
	v_lshl_add_u32 v140, v135, 3, s0
	v_ashrrev_i32_e32 v135, 31, v134
	v_ashrrev_i32_e32 v65, 31, v64
	v_lshlrev_b64 v[142:143], 14, v[134:135]
	v_ashrrev_i32_e32 v141, 31, v140
	v_lshlrev_b64 v[64:65], 14, v[64:65]
	v_cvt_pk_bf16_f32 v124, v124, v125
	v_cvt_pk_bf16_f32 v125, v126, v127
	v_cvt_pk_bf16_f32 v126, v120, v121
	v_cvt_pk_bf16_f32 v127, v122, v123
	v_lshl_add_u64 v[122:123], s[26:27], 0, v[142:143]
	v_lshlrev_b64 v[120:121], 1, v[140:141]
	v_cvt_pk_bf16_f32 v112, v112, v113
	v_cvt_pk_bf16_f32 v113, v114, v115
	v_cvt_pk_bf16_f32 v114, v104, v105
	v_add_u32_e32 v104, 16, v134
	v_cvt_pk_bf16_f32 v60, v60, v61
	v_cvt_pk_bf16_f32 v61, v62, v63
	v_cvt_pk_bf16_f32 v62, v56, v57
	v_lshl_add_u64 v[56:57], s[26:27], 0, v[64:65]
	v_cvt_pk_bf16_f32 v48, v48, v49
	v_cvt_pk_bf16_f32 v49, v50, v51
	v_cvt_pk_bf16_f32 v50, v40, v41
	v_add_u32_e32 v40, 0x90, v134
	v_lshl_add_u64 v[122:123], v[122:123], 0, v[120:121]
	v_ashrrev_i32_e32 v105, 31, v104
	v_lshl_add_u64 v[56:57], v[56:57], 0, v[120:121]
	v_ashrrev_i32_e32 v41, 31, v40
	v_cvt_pk_bf16_f32 v115, v106, v107
	global_store_dwordx4 v[122:123], v[112:115], off offset:256
	v_cvt_pk_bf16_f32 v51, v42, v43
	global_store_dwordx4 v[56:57], v[48:51], off offset:256
	v_cvt_pk_bf16_f32 v106, v108, v109
	v_cvt_pk_bf16_f32 v96, v96, v97
	v_cvt_pk_bf16_f32 v97, v98, v99
	s_nop 0
	v_lshlrev_b64 v[112:113], 14, v[104:105]
	v_lshl_add_u64 v[108:109], s[26:27], 0, v[112:113]
	v_lshlrev_b64 v[48:49], 14, v[40:41]
	v_cvt_pk_bf16_f32 v98, v88, v89
	v_add_u32_e32 v88, 32, v134
	v_cvt_pk_bf16_f32 v42, v44, v45
	v_lshl_add_u64 v[44:45], s[26:27], 0, v[48:49]
	v_cvt_pk_bf16_f32 v32, v32, v33
	v_cvt_pk_bf16_f32 v33, v34, v35
	v_cvt_pk_bf16_f32 v34, v24, v25
	v_add_u32_e32 v24, 0xa0, v134
	v_lshl_add_u64 v[108:109], v[108:109], 0, v[120:121]
	v_ashrrev_i32_e32 v89, 31, v88
	v_lshl_add_u64 v[44:45], v[44:45], 0, v[120:121]
	v_ashrrev_i32_e32 v25, 31, v24
	v_cvt_pk_bf16_f32 v99, v90, v91
	global_store_dwordx4 v[108:109], v[96:99], off offset:256
	v_cvt_pk_bf16_f32 v35, v26, v27
	global_store_dwordx4 v[44:45], v[32:35], off offset:256
	v_cvt_pk_bf16_f32 v90, v92, v93
	v_cvt_pk_bf16_f32 v80, v80, v81
	v_cvt_pk_bf16_f32 v81, v82, v83
	s_nop 0
	v_lshlrev_b64 v[96:97], 14, v[88:89]
	v_lshl_add_u64 v[92:93], s[26:27], 0, v[96:97]
	v_lshlrev_b64 v[32:33], 14, v[24:25]
	v_cvt_pk_bf16_f32 v82, v72, v73
	v_add_u32_e32 v72, 48, v134
	v_cvt_pk_bf16_f32 v26, v28, v29
	v_lshl_add_u64 v[28:29], s[26:27], 0, v[32:33]
	v_cvt_pk_bf16_f32 v16, v16, v17
	v_cvt_pk_bf16_f32 v17, v18, v19
	v_cvt_pk_bf16_f32 v18, v8, v9
	v_add_u32_e32 v8, 0xb0, v134
	v_lshl_add_u64 v[92:93], v[92:93], 0, v[120:121]
	v_ashrrev_i32_e32 v73, 31, v72
	v_lshl_add_u64 v[28:29], v[28:29], 0, v[120:121]
	v_ashrrev_i32_e32 v9, 31, v8
	v_cvt_pk_bf16_f32 v83, v74, v75
	global_store_dwordx4 v[92:93], v[80:83], off offset:256
	v_cvt_pk_bf16_f32 v19, v10, v11
	global_store_dwordx4 v[28:29], v[16:19], off offset:256
	v_cvt_pk_bf16_f32 v74, v76, v77
	v_cvt_pk_bf16_f32 v10, v12, v13
	s_and_b64 vcc, exec, s[12:13]
	v_lshlrev_b64 v[80:81], 14, v[72:73]
	v_lshlrev_b64 v[16:17], 14, v[8:9]
	v_lshl_add_u64 v[76:77], s[26:27], 0, v[80:81]
	v_lshl_add_u64 v[12:13], s[26:27], 0, v[16:17]
	v_lshl_add_u64 v[76:77], v[76:77], 0, v[120:121]
	v_lshl_add_u64 v[12:13], v[12:13], 0, v[120:121]
	s_mov_b32 s46, s8
	s_mov_b32 s22, s16
	s_mov_b64 s[62:63], s[20:21]
	s_mov_b64 s[64:65], s[18:19]
	global_store_dwordx4 v[122:123], v[124:127], off
	v_cvt_pk_bf16_f32 v104, v116, v117
	v_cvt_pk_bf16_f32 v105, v118, v119
	v_cvt_pk_bf16_f32 v107, v110, v111
	global_store_dwordx4 v[108:109], v[104:107], off
	v_cvt_pk_bf16_f32 v88, v100, v101
	v_cvt_pk_bf16_f32 v89, v102, v103
	v_cvt_pk_bf16_f32 v91, v94, v95
	global_store_dwordx4 v[92:93], v[88:91], off
	v_cvt_pk_bf16_f32 v72, v84, v85
	v_cvt_pk_bf16_f32 v73, v86, v87
	v_cvt_pk_bf16_f32 v75, v78, v79
	global_store_dwordx4 v[76:77], v[72:75], off
	v_cvt_pk_bf16_f32 v71, v66, v67
	global_store_dwordx4 v[76:77], v[68:71], off offset:256
	v_cvt_pk_bf16_f32 v63, v58, v59
	global_store_dwordx4 v[56:57], v[60:63], off
	v_cvt_pk_bf16_f32 v40, v52, v53
	v_cvt_pk_bf16_f32 v41, v54, v55
	v_cvt_pk_bf16_f32 v43, v46, v47
	global_store_dwordx4 v[44:45], v[40:43], off
	v_cvt_pk_bf16_f32 v24, v36, v37
	v_cvt_pk_bf16_f32 v25, v38, v39
	v_cvt_pk_bf16_f32 v27, v30, v31
	global_store_dwordx4 v[28:29], v[24:27], off
	v_cvt_pk_bf16_f32 v8, v20, v21
	v_cvt_pk_bf16_f32 v9, v22, v23
	v_cvt_pk_bf16_f32 v11, v14, v15
	global_store_dwordx4 v[12:13], v[8:11], off
	v_cvt_pk_bf16_f32 v4, v4, v5
	v_cvt_pk_bf16_f32 v5, v6, v7
	v_cvt_pk_bf16_f32 v6, v0, v1
	v_cvt_pk_bf16_f32 v7, v2, v3
	global_store_dwordx4 v[12:13], v[4:7], off offset:256
	s_cbranch_vccz .LBB0_101
	s_setprio 0
	s_waitcnt vmcnt(0)
	v_readlane_b32 s44, v255, 6
	s_cmpk_gt_u32 s4, 0xff
	v_readlane_b32 s45, v255, 7
	s_cbranch_scc1 .LBB0_108
	s_barrier

; #define G_STAGE(bufoff, gbase, voff) do { _Pragma("unroll") for (int _i = 0; _i < 2; ++_i) \
;         __builtin_amdgcn_global_load_lds((const unsigned*)((const char*)(gbase) + (voff)[_i]), (LAS unsigned*)(lds + (bufoff) + ldsw + _i * 8192), 16, 0, 0); } while (0)
; #define G_LDA(dst, b, h) do { _Pragma("unroll") for (int m = 0; m < 4; ++m) _Pragma("unroll") for (int k = 0; k < 2; ++k) dst[m][k] = *(const LAS bf16x8*)(lds + G_SA(b, h) + aoff + m * 2048 + k * 1024); } while (0)
; #define G_LDB(dst, b, h) do { _Pragma("unroll") for (int n = 0; n < 2; ++n) _Pragma("unroll") for (int k = 0; k < 2; ++k) dst[n][k] = *(const LAS bf16x8*)(lds + G_SB(b, h) + boff + n * 2048 + k * 1024); } while (0)
; #define G_MMA(ai, bj, At, Bt) do { __builtin_amdgcn_s_setprio(1); _Pragma("unroll") for (int m = 0; m < 4; ++m) _Pragma("unroll") for (int n = 0; n < 2; ++n) _Pragma("unroll") for (int k = 0; k < 2; ++k) \
;         acc[ai][bj][m][n] = __builtin_amdgcn_mfma_f32_16x16x32_bf16(Bt[n][k], At[m][k], acc[ai][bj][m][n], 0, 0, 0); __builtin_amdgcn_s_setprio(0); } while (0)
; #define G_WAIT_L(n) asm volatile("s_waitcnt lgkmcnt(" #n ")" ::: "memory")
; #define G_BAR __builtin_amdgcn_s_barrier()
; #define G_SCHED __builtin_amdgcn_sched_barrier(0)
; template <class J>
; DI void gemm_phase(LAS unsigned char* lds, const J& job) {
;     ...
;     for (int t = 0; t < nt; t += 2) {
;       const bool last = (t == nt - 2);
;       const char* a1 = cA + G_KT(t + 1);
;       const char* a2 = last ? nA + G_KT(0) : cA + G_KT(t + 2); const char* b2 = last ? nB + G_KT(0) : cB + G_KT(t + 2);
;       const char* a3 = last ? nA + G_KT(1) : cA + G_KT(t + 3); const char* b3 = last ? nB + G_KT(1) : cB + G_KT(t + 3);
;       G_LDB(B0, 0, 0); G_SCHED; G_LDA(At, 0, 0); G_STAGE(G_SA(1, 1), a1 + hstepA, voffA);
;       G_WAIT_L(8); G_BAR; G_WAIT_L(0); G_MMA(0, 0, At, B0); G_BAR; G_SCHED;
;       G_LDB(B1, 0, 1); G_STAGE(G_SB(0, 0), b2, voffB);
;       G_BAR; G_WAIT_L(0); G_MMA(0, 1, At, B1); G_BAR;
;       G_LDA(At, 0, 1); G_STAGE(G_SA(0, 0), a2, voffA);
;       G_BAR; G_WAIT_L(0); G_MMA(1, 0, At, B0); G_BAR; G_SCHED;
.LBB0_282:
	s_add_i32 s1, s56, 0xffffff80
	s_and_b32 s0, s7, 0xf80
	s_and_b32 s1, s1, 0xf00
	s_add_u32 s10, s68, s1
	s_addc_u32 s11, s69, 0
	s_add_u32 s1, s66, s1
	s_addc_u32 s57, s67, 0
	s_and_b32 s70, s56, 0xf80
	s_add_u32 s71, s68, s70
	s_addc_u32 s72, s69, 0
	s_add_u32 s70, s66, s70
	s_addc_u32 s80, s67, 0
	s_cmp_eq_u32 s6, 28
	s_cselect_b32 s75, s46, s11
	s_cselect_b32 s74, s21, s10
	s_cselect_b32 s77, s96, s57
	s_cselect_b32 s76, s47, s1
	s_cselect_b32 s73, s97, s72
	s_cselect_b32 s72, s33, s71
	s_cselect_b32 s71, vcc_hi, s80
	s_cselect_b32 s70, vcc_lo, s70
	s_add_i32 s1, s84, 0x100
	v_add_u32_e32 v142, s1, v150
	ds_read_b128 v[134:137], v142
	ds_read_b128 v[138:141], v142 offset:1024
	ds_read_b128 v[152:155], v142 offset:2048
	ds_read_b128 v[156:159], v142 offset:3072
	s_add_u32 s10, s9, s0
	s_addc_u32 s11, s19, 0
	v_lshl_add_u64 v[142:143], s[10:11], 0, v[128:129]
	s_add_i32 m0, s15, 0xc000
	ds_read_b128 v[160:163], v151
	ds_read_b128 v[164:167], v151 offset:1024
	ds_read_b128 v[168:171], v151 offset:2048
	ds_read_b128 v[172:175], v151 offset:3072
	ds_read_b128 v[176:179], v151 offset:4096
	ds_read_b128 v[180:183], v151 offset:5120
	ds_read_b128 v[184:187], v151 offset:6144
	ds_read_b128 v[188:191], v151 offset:7168
	global_load_lds_dwordx4 v[142:143], off
	v_lshl_add_u64 v[142:143], s[10:11], 0, v[130:131]
	s_add_i32 m0, s15, 0xe000
	s_nop 0
	global_load_lds_dwordx4 v[142:143], off
	s_waitcnt lgkmcnt(8)
	s_barrier
	s_waitcnt lgkmcnt(7)
	v_mfma_f32_16x16x32_bf16 v[124:127], v[134:137], v[160:163], v[124:127]
	v_mfma_f32_16x16x32_bf16 v[120:123], v[152:155], v[160:163], v[120:123]
	s_waitcnt lgkmcnt(5)
	v_mfma_f32_16x16x32_bf16 v[108:111], v[134:137], v[168:171], v[108:111]
	v_mfma_f32_16x16x32_bf16 v[104:107], v[152:155], v[168:171], v[104:107]
	s_waitcnt lgkmcnt(3)
	v_mfma_f32_16x16x32_bf16 v[92:95], v[134:137], v[176:179], v[92:95]
	v_mfma_f32_16x16x32_bf16 v[88:91], v[152:155], v[176:179], v[88:91]
	s_waitcnt lgkmcnt(1)
	v_mfma_f32_16x16x32_bf16 v[76:79], v[134:137], v[184:187], v[76:79]
	v_mfma_f32_16x16x32_bf16 v[72:75], v[152:155], v[184:187], v[72:75]
	v_mfma_f32_16x16x32_bf16 v[124:127], v[138:141], v[164:167], v[124:127]
	v_mfma_f32_16x16x32_bf16 v[120:123], v[156:159], v[164:167], v[120:123]
	v_mfma_f32_16x16x32_bf16 v[108:111], v[138:141], v[172:175], v[108:111]
	v_mfma_f32_16x16x32_bf16 v[104:107], v[156:159], v[172:175], v[104:107]
	v_mfma_f32_16x16x32_bf16 v[92:95], v[138:141], v[180:183], v[92:95]
	v_mfma_f32_16x16x32_bf16 v[88:91], v[156:159], v[180:183], v[88:91]
	s_waitcnt lgkmcnt(0)
	v_mfma_f32_16x16x32_bf16 v[76:79], v[138:141], v[188:191], v[76:79]
	v_mfma_f32_16x16x32_bf16 v[72:75], v[156:159], v[188:191], v[72:75]
	s_barrier
	s_add_i32 s0, s85, 0x100
	v_add_u32_e32 v142, s0, v150
	s_add_i32 s1, s1, s5
	ds_read_b128 v[192:195], v142
	ds_read_b128 v[196:199], v142 offset:1024
	ds_read_b128 v[200:203], v142 offset:2048
	ds_read_b128 v[204:207], v142 offset:3072
	v_lshl_add_u64 v[142:143], s[76:77], 0, v[146:147]
	s_mov_b32 m0, s1
	s_nop 0
	global_load_lds_dwordx4 v[142:143], off
	v_lshl_add_u64 v[142:143], s[76:77], 0, v[132:133]
	s_add_i32 m0, s1, 0x2000
	s_nop 0
	global_load_lds_dwordx4 v[142:143], off
	s_barrier
	s_waitcnt lgkmcnt(0)
	v_mfma_f32_16x16x32_bf16 v[116:119], v[192:195], v[160:163], v[116:119]
	v_mfma_f32_16x16x32_bf16 v[112:115], v[200:203], v[160:163], v[112:115]
	v_mfma_f32_16x16x32_bf16 v[100:103], v[192:195], v[168:171], v[100:103]
	v_mfma_f32_16x16x32_bf16 v[96:99], v[200:203], v[168:171], v[96:99]
	v_mfma_f32_16x16x32_bf16 v[84:87], v[192:195], v[176:179], v[84:87]
	v_mfma_f32_16x16x32_bf16 v[80:83], v[200:203], v[176:179], v[80:83]
	v_mfma_f32_16x16x32_bf16 v[68:71], v[192:195], v[184:187], v[68:71]
	v_mfma_f32_16x16x32_bf16 v[64:67], v[200:203], v[184:187], v[64:67]
	v_mfma_f32_16x16x32_bf16 v[116:119], v[196:199], v[164:167], v[116:119]
	v_mfma_f32_16x16x32_bf16 v[112:115], v[204:207], v[164:167], v[112:115]
	v_mfma_f32_16x16x32_bf16 v[100:103], v[196:199], v[172:175], v[100:103]
	v_mfma_f32_16x16x32_bf16 v[96:99], v[204:207], v[172:175], v[96:99]
	v_mfma_f32_16x16x32_bf16 v[84:87], v[196:199], v[180:183], v[84:87]
	v_mfma_f32_16x16x32_bf16 v[80:83], v[204:207], v[180:183], v[80:83]
	v_mfma_f32_16x16x32_bf16 v[68:71], v[196:199], v[188:191], v[68:71]
	v_mfma_f32_16x16x32_bf16 v[64:67], v[204:207], v[188:191], v[64:67]
	s_mov_b32 m0, s15
	v_lshl_add_u64 v[142:143], s[74:75], 0, v[128:129]
	s_barrier
	ds_read_b128 v[160:163], v151 offset:16384
	ds_read_b128 v[164:167], v151 offset:17408
	ds_read_b128 v[168:171], v151 offset:18432
	ds_read_b128 v[172:175], v151 offset:19456
	ds_read_b128 v[176:179], v151 offset:20480
	ds_read_b128 v[180:183], v151 offset:21504
	ds_read_b128 v[184:187], v151 offset:22528
	ds_read_b128 v[188:191], v151 offset:23552
	global_load_lds_dwordx4 v[142:143], off
	v_lshl_add_u64 v[142:143], s[74:75], 0, v[130:131]
	s_mov_b32 m0, s24
	s_nop 0
	global_load_lds_dwordx4 v[142:143], off
	s_barrier
	s_waitcnt lgkmcnt(0)
	v_mfma_f32_16x16x32_bf16 v[60:63], v[134:137], v[160:163], v[60:63]
	v_mfma_f32_16x16x32_bf16 v[56:59], v[152:155], v[160:163], v[56:59]
	v_mfma_f32_16x16x32_bf16 v[44:47], v[134:137], v[168:171], v[44:47]
	v_mfma_f32_16x16x32_bf16 v[40:43], v[152:155], v[168:171], v[40:43]
	v_mfma_f32_16x16x32_bf16 v[28:31], v[134:137], v[176:179], v[28:31]
	v_mfma_f32_16x16x32_bf16 v[24:27], v[152:155], v[176:179], v[24:27]
	v_mfma_f32_16x16x32_bf16 v[12:15], v[134:137], v[184:187], v[12:15]
	v_mfma_f32_16x16x32_bf16 v[8:11], v[152:155], v[184:187], v[8:11]
	v_mfma_f32_16x16x32_bf16 v[60:63], v[138:141], v[164:167], v[60:63]
	v_mfma_f32_16x16x32_bf16 v[56:59], v[156:159], v[164:167], v[56:59]
	v_mfma_f32_16x16x32_bf16 v[44:47], v[138:141], v[172:175], v[44:47]
	v_mfma_f32_16x16x32_bf16 v[40:43], v[156:159], v[172:175], v[40:43]
	v_mfma_f32_16x16x32_bf16 v[28:31], v[138:141], v[180:183], v[28:31]
	v_mfma_f32_16x16x32_bf16 v[24:27], v[156:159], v[180:183], v[24:27]
	v_mfma_f32_16x16x32_bf16 v[12:15], v[138:141], v[188:191], v[12:15]
	v_mfma_f32_16x16x32_bf16 v[8:11], v[156:159], v[188:191], v[8:11]
	s_barrier
; #define G_STAGE(bufoff, gbase, voff) do { _Pragma("unroll") for (int _i = 0; _i < 2; ++_i) \
;         __builtin_amdgcn_global_load_lds((const unsigned*)((const char*)(gbase) + (voff)[_i]), (LAS unsigned*)(lds + (bufoff) + ldsw + _i * 8192), 16, 0, 0); } while (0)
; #define G_LDA(dst, b, h) do { _Pragma("unroll") for (int m = 0; m < 4; ++m) _Pragma("unroll") for (int k = 0; k < 2; ++k) dst[m][k] = *(const LAS bf16x8*)(lds + G_SA(b, h) + aoff + m * 2048 + k * 1024); } while (0)
; #define G_LDB(dst, b, h) do { _Pragma("unroll") for (int n = 0; n < 2; ++n) _Pragma("unroll") for (int k = 0; k < 2; ++k) dst[n][k] = *(const LAS bf16x8*)(lds + G_SB(b, h) + boff + n * 2048 + k * 1024); } while (0)
; #define G_MMA(ai, bj, At, Bt) do { __builtin_amdgcn_s_setprio(1); _Pragma("unroll") for (int m = 0; m < 4; ++m) _Pragma("unroll") for (int n = 0; n < 2; ++n) _Pragma("unroll") for (int k = 0; k < 2; ++k) \
;         acc[ai][bj][m][n] = __builtin_amdgcn_mfma_f32_16x16x32_bf16(Bt[n][k], At[m][k], acc[ai][bj][m][n], 0, 0, 0); __builtin_amdgcn_s_setprio(0); } while (0)
; #define G_WAIT_V(n) asm volatile("s_waitcnt vmcnt(" #n ")" ::: "memory")
; #define G_WAIT_L(n) asm volatile("s_waitcnt lgkmcnt(" #n ")" ::: "memory")
; #define G_BAR __builtin_amdgcn_s_barrier()
; #define G_SCHED __builtin_amdgcn_sched_barrier(0)
; template <class J>
; DI void gemm_phase(LAS unsigned char* lds, const J& job) {
;     ...
;       G_STAGE(G_SB(0, 1), b2 + hstepB, voffB);
;       G_WAIT_V(6); G_BAR; G_MMA(1, 1, At, B1); G_BAR;
;       G_LDB(B0, 1, 0); G_SCHED; G_LDA(At, 1, 0); G_STAGE(G_SA(0, 1), a2 + hstepA, voffA);
;       G_WAIT_L(8); G_BAR; G_WAIT_L(0); G_MMA(0, 0, At, B0); G_BAR; G_SCHED;
;       G_LDB(B1, 1, 1); G_STAGE(G_SB(1, 0), b3, voffB);
;       G_BAR; G_WAIT_L(0); G_MMA(0, 1, At, B1); G_BAR;
;       G_LDA(At, 1, 1); G_STAGE(G_SA(1, 0), a3, voffA);
	s_add_u32 s10, s76, 0x80000
	s_addc_u32 s11, s77, 0
	s_add_i32 s0, s0, s5
	v_lshl_add_u64 v[134:135], s[10:11], 0, v[146:147]
	s_mov_b32 m0, s0
	s_nop 0
	global_load_lds_dwordx4 v[134:135], off
	v_lshl_add_u64 v[134:135], s[10:11], 0, v[132:133]
	s_add_i32 m0, s0, 0x2000
	s_nop 0
	global_load_lds_dwordx4 v[134:135], off
	s_waitcnt vmcnt(6)
	s_barrier
	v_mfma_f32_16x16x32_bf16 v[52:55], v[192:195], v[160:163], v[52:55]
	v_mfma_f32_16x16x32_bf16 v[48:51], v[200:203], v[160:163], v[48:51]
	v_mfma_f32_16x16x32_bf16 v[36:39], v[192:195], v[168:171], v[36:39]
	v_mfma_f32_16x16x32_bf16 v[32:35], v[200:203], v[168:171], v[32:35]
	v_mfma_f32_16x16x32_bf16 v[20:23], v[192:195], v[176:179], v[20:23]
	v_mfma_f32_16x16x32_bf16 v[16:19], v[200:203], v[176:179], v[16:19]
	v_mfma_f32_16x16x32_bf16 v[4:7], v[192:195], v[184:187], v[4:7]
	v_mfma_f32_16x16x32_bf16 v[0:3], v[200:203], v[184:187], v[0:3]
	v_mfma_f32_16x16x32_bf16 v[52:55], v[196:199], v[164:167], v[52:55]
	v_mfma_f32_16x16x32_bf16 v[48:51], v[204:207], v[164:167], v[48:51]
	v_mfma_f32_16x16x32_bf16 v[36:39], v[196:199], v[172:175], v[36:39]
	v_mfma_f32_16x16x32_bf16 v[32:35], v[204:207], v[172:175], v[32:35]
	v_mfma_f32_16x16x32_bf16 v[20:23], v[196:199], v[180:183], v[20:23]
	v_mfma_f32_16x16x32_bf16 v[16:19], v[204:207], v[180:183], v[16:19]
	v_mfma_f32_16x16x32_bf16 v[4:7], v[196:199], v[188:191], v[4:7]
	v_mfma_f32_16x16x32_bf16 v[0:3], v[204:207], v[188:191], v[0:3]
	s_add_i32 s0, s88, 0x100
	v_add_u32_e32 v142, s0, v150
	s_barrier
	ds_read_b128 v[134:137], v142
	ds_read_b128 v[138:141], v142 offset:1024
	ds_read_b128 v[152:155], v142 offset:2048
	ds_read_b128 v[156:159], v142 offset:3072
	s_add_u32 s10, s74, 0x80000
	s_addc_u32 s11, s75, 0
	s_mov_b32 m0, s25
	v_lshl_add_u64 v[142:143], s[10:11], 0, v[128:129]
	ds_read_b128 v[160:163], v151 offset:32768
	ds_read_b128 v[164:167], v151 offset:33792
	ds_read_b128 v[168:171], v151 offset:34816
	ds_read_b128 v[172:175], v151 offset:35840
	ds_read_b128 v[176:179], v151 offset:36864
	ds_read_b128 v[180:183], v151 offset:37888
	ds_read_b128 v[184:187], v151 offset:38912
	ds_read_b128 v[188:191], v151 offset:39936
	global_load_lds_dwordx4 v[142:143], off
	v_lshl_add_u64 v[142:143], s[10:11], 0, v[130:131]
	s_mov_b32 m0, s36
	s_nop 0
	global_load_lds_dwordx4 v[142:143], off
	s_waitcnt lgkmcnt(8)
	s_barrier
	s_waitcnt lgkmcnt(7)
	v_mfma_f32_16x16x32_bf16 v[124:127], v[134:137], v[160:163], v[124:127]
	v_mfma_f32_16x16x32_bf16 v[120:123], v[152:155], v[160:163], v[120:123]
	s_waitcnt lgkmcnt(5)
	v_mfma_f32_16x16x32_bf16 v[108:111], v[134:137], v[168:171], v[108:111]
	v_mfma_f32_16x16x32_bf16 v[104:107], v[152:155], v[168:171], v[104:107]
	s_waitcnt lgkmcnt(3)
	v_mfma_f32_16x16x32_bf16 v[92:95], v[134:137], v[176:179], v[92:95]
	v_mfma_f32_16x16x32_bf16 v[88:91], v[152:155], v[176:179], v[88:91]
	s_waitcnt lgkmcnt(1)
	v_mfma_f32_16x16x32_bf16 v[76:79], v[134:137], v[184:187], v[76:79]
	v_mfma_f32_16x16x32_bf16 v[72:75], v[152:155], v[184:187], v[72:75]
	v_mfma_f32_16x16x32_bf16 v[124:127], v[138:141], v[164:167], v[124:127]
	v_mfma_f32_16x16x32_bf16 v[120:123], v[156:159], v[164:167], v[120:123]
	v_mfma_f32_16x16x32_bf16 v[108:111], v[138:141], v[172:175], v[108:111]
	v_mfma_f32_16x16x32_bf16 v[104:107], v[156:159], v[172:175], v[104:107]
	v_mfma_f32_16x16x32_bf16 v[92:95], v[138:141], v[180:183], v[92:95]
	v_mfma_f32_16x16x32_bf16 v[88:91], v[156:159], v[180:183], v[88:91]
	s_waitcnt lgkmcnt(0)
	v_mfma_f32_16x16x32_bf16 v[76:79], v[138:141], v[188:191], v[76:79]
	v_mfma_f32_16x16x32_bf16 v[72:75], v[156:159], v[188:191], v[72:75]
	s_barrier
	s_add_i32 s1, s89, 0x100
	v_add_u32_e32 v142, s1, v150
	s_add_i32 s0, s0, s5
	ds_read_b128 v[192:195], v142
	ds_read_b128 v[196:199], v142 offset:1024
	ds_read_b128 v[200:203], v142 offset:2048
	ds_read_b128 v[204:207], v142 offset:3072
	v_lshl_add_u64 v[142:143], s[70:71], 0, v[146:147]
	s_mov_b32 m0, s0
	s_nop 0
	global_load_lds_dwordx4 v[142:143], off
	v_lshl_add_u64 v[142:143], s[70:71], 0, v[132:133]
	s_add_i32 m0, s0, 0x2000
	s_nop 0
	global_load_lds_dwordx4 v[142:143], off
	s_barrier
	s_waitcnt lgkmcnt(0)
	v_mfma_f32_16x16x32_bf16 v[116:119], v[192:195], v[160:163], v[116:119]
	v_mfma_f32_16x16x32_bf16 v[112:115], v[200:203], v[160:163], v[112:115]
	v_mfma_f32_16x16x32_bf16 v[100:103], v[192:195], v[168:171], v[100:103]
	v_mfma_f32_16x16x32_bf16 v[96:99], v[200:203], v[168:171], v[96:99]
	v_mfma_f32_16x16x32_bf16 v[84:87], v[192:195], v[176:179], v[84:87]
	v_mfma_f32_16x16x32_bf16 v[80:83], v[200:203], v[176:179], v[80:83]
	v_mfma_f32_16x16x32_bf16 v[68:71], v[192:195], v[184:187], v[68:71]
	v_mfma_f32_16x16x32_bf16 v[64:67], v[200:203], v[184:187], v[64:67]
	v_mfma_f32_16x16x32_bf16 v[116:119], v[196:199], v[164:167], v[116:119]
	v_mfma_f32_16x16x32_bf16 v[112:115], v[204:207], v[164:167], v[112:115]
	v_mfma_f32_16x16x32_bf16 v[100:103], v[196:199], v[172:175], v[100:103]
	v_mfma_f32_16x16x32_bf16 v[96:99], v[204:207], v[172:175], v[96:99]
	v_mfma_f32_16x16x32_bf16 v[84:87], v[196:199], v[180:183], v[84:87]
	v_mfma_f32_16x16x32_bf16 v[80:83], v[204:207], v[180:183], v[80:83]
	v_mfma_f32_16x16x32_bf16 v[68:71], v[196:199], v[188:191], v[68:71]
	v_mfma_f32_16x16x32_bf16 v[64:67], v[204:207], v[188:191], v[64:67]
	s_mov_b32 m0, s45
	v_lshl_add_u64 v[142:143], s[72:73], 0, v[128:129]
	s_barrier
; DI unsigned pk2(float lo, float hi) { unsigned r; asm("v_cvt_pk_bf16_f32 %0, %1, %2" : "=v"(r) : "v"(lo), "v"(hi)); return r; }
; #define G_STAGE(bufoff, gbase, voff) do { _Pragma("unroll") for (int _i = 0; _i < 2; ++_i) \
;         __builtin_amdgcn_global_load_lds((const unsigned*)((const char*)(gbase) + (voff)[_i]), (LAS unsigned*)(lds + (bufoff) + ldsw + _i * 8192), 16, 0, 0); } while (0)
; #define G_LDA(dst, b, h) do { _Pragma("unroll") for (int m = 0; m < 4; ++m) _Pragma("unroll") for (int k = 0; k < 2; ++k) dst[m][k] = *(const LAS bf16x8*)(lds + G_SA(b, h) + aoff + m * 2048 + k * 1024); } while (0)
; #define G_MMA(ai, bj, At, Bt) do { __builtin_amdgcn_s_setprio(1); _Pragma("unroll") for (int m = 0; m < 4; ++m) _Pragma("unroll") for (int n = 0; n < 2; ++n) _Pragma("unroll") for (int k = 0; k < 2; ++k) \
;         acc[ai][bj][m][n] = __builtin_amdgcn_mfma_f32_16x16x32_bf16(Bt[n][k], At[m][k], acc[ai][bj][m][n], 0, 0, 0); __builtin_amdgcn_s_setprio(0); } while (0)
; #define G_WAIT_V(n) asm volatile("s_waitcnt vmcnt(" #n ")" ::: "memory")
; #define G_WAIT_L(n) asm volatile("s_waitcnt lgkmcnt(" #n ")" ::: "memory")
; #define G_BAR __builtin_amdgcn_s_barrier()
; #define G_SCHED __builtin_amdgcn_sched_barrier(0)
; template <class J>
; DI void gemm_phase(LAS unsigned char* lds, const J& job) {
;     ...
;       G_LDA(At, 1, 1); G_STAGE(G_SA(1, 0), a3, voffA);
;       G_BAR; G_WAIT_L(0); G_MMA(1, 0, At, B0); G_BAR; G_SCHED;
;       G_STAGE(G_SB(1, 1), b3 + hstepB, voffB);
;       G_WAIT_V(6); G_BAR; G_MMA(1, 1, At, B1); G_BAR;
;   DI void epi(const Acc& acc, const Unit& u, int wr, int wc, int fr, int fq) const {
;     ...
;           const int col = u.pn * 256 + bj * HALF + wc * 32 + 8 * fq;
;           const f32x4 v0 = acc[ai][bj][m][0], v1 = acc[ai][bj][m][1];
;           const int row = u.pm * 256 + rl;
;           u32x4 o; o.x = pk2(v0.x, v0.y); o.y = pk2(v0.z, v0.w); o.z = pk2(v1.x, v1.y); o.w = pk2(v1.z, v1.w);
;           *(u32x4*)(proj + (size_t)row * NPROJ + col) = o;
;           if (u.pn >= 8 && u.pn < 12) {
;             const int isv = u.pn >= 10; const int cc = col - (isv ? C_BV : C_BK);
;             float* dst = out + (isv ? O_VP : O_KP) + ((size_t)l * TP + row) * 512 + cc;
;             *(f32x4*)dst = v0; *(f32x4*)(dst + 4) = v1;
	ds_read_b128 v[160:163], v151 offset:49152
	ds_read_b128 v[164:167], v151 offset:50176
	ds_read_b128 v[168:171], v151 offset:51200
	ds_read_b128 v[172:175], v151 offset:52224
	ds_read_b128 v[176:179], v151 offset:53248
	ds_read_b128 v[180:183], v151 offset:54272
	ds_read_b128 v[184:187], v151 offset:55296
	ds_read_b128 v[188:191], v151 offset:56320
	global_load_lds_dwordx4 v[142:143], off
	v_lshl_add_u64 v[142:143], s[72:73], 0, v[130:131]
	s_mov_b32 m0, s65
	s_nop 0
	global_load_lds_dwordx4 v[142:143], off
	s_barrier
	s_waitcnt lgkmcnt(0)
	v_mfma_f32_16x16x32_bf16 v[60:63], v[134:137], v[160:163], v[60:63]
	v_mfma_f32_16x16x32_bf16 v[56:59], v[152:155], v[160:163], v[56:59]
	v_mfma_f32_16x16x32_bf16 v[44:47], v[134:137], v[168:171], v[44:47]
	v_mfma_f32_16x16x32_bf16 v[40:43], v[152:155], v[168:171], v[40:43]
	v_mfma_f32_16x16x32_bf16 v[28:31], v[134:137], v[176:179], v[28:31]
	v_mfma_f32_16x16x32_bf16 v[24:27], v[152:155], v[176:179], v[24:27]
	v_mfma_f32_16x16x32_bf16 v[12:15], v[134:137], v[184:187], v[12:15]
	v_mfma_f32_16x16x32_bf16 v[8:11], v[152:155], v[184:187], v[8:11]
	v_mfma_f32_16x16x32_bf16 v[60:63], v[138:141], v[164:167], v[60:63]
	v_mfma_f32_16x16x32_bf16 v[56:59], v[156:159], v[164:167], v[56:59]
	v_mfma_f32_16x16x32_bf16 v[44:47], v[138:141], v[172:175], v[44:47]
	v_mfma_f32_16x16x32_bf16 v[40:43], v[156:159], v[172:175], v[40:43]
	v_mfma_f32_16x16x32_bf16 v[28:31], v[138:141], v[180:183], v[28:31]
	v_mfma_f32_16x16x32_bf16 v[24:27], v[156:159], v[180:183], v[24:27]
	v_mfma_f32_16x16x32_bf16 v[12:15], v[138:141], v[188:191], v[12:15]
	v_mfma_f32_16x16x32_bf16 v[8:11], v[156:159], v[188:191], v[8:11]
	s_barrier
	s_add_u32 s10, s70, 0x80000
	s_addc_u32 s11, s71, 0
	s_add_i32 s0, s1, s5
	v_lshl_add_u64 v[134:135], s[10:11], 0, v[146:147]
	s_mov_b32 m0, s0
	s_nop 0
	global_load_lds_dwordx4 v[134:135], off
	v_lshl_add_u64 v[134:135], s[10:11], 0, v[132:133]
	s_add_i32 m0, s0, 0x2000
	s_nop 0
	global_load_lds_dwordx4 v[134:135], off
	s_waitcnt vmcnt(6)
	s_barrier
	v_mfma_f32_16x16x32_bf16 v[52:55], v[192:195], v[160:163], v[52:55]
	v_mfma_f32_16x16x32_bf16 v[48:51], v[200:203], v[160:163], v[48:51]
	v_mfma_f32_16x16x32_bf16 v[36:39], v[192:195], v[168:171], v[36:39]
	v_mfma_f32_16x16x32_bf16 v[32:35], v[200:203], v[168:171], v[32:35]
	v_mfma_f32_16x16x32_bf16 v[20:23], v[192:195], v[176:179], v[20:23]
	v_mfma_f32_16x16x32_bf16 v[16:19], v[200:203], v[176:179], v[16:19]
	v_mfma_f32_16x16x32_bf16 v[4:7], v[192:195], v[184:187], v[4:7]
	v_mfma_f32_16x16x32_bf16 v[0:3], v[200:203], v[184:187], v[0:3]
	v_mfma_f32_16x16x32_bf16 v[52:55], v[196:199], v[164:167], v[52:55]
	v_mfma_f32_16x16x32_bf16 v[48:51], v[204:207], v[164:167], v[48:51]
	v_mfma_f32_16x16x32_bf16 v[36:39], v[196:199], v[172:175], v[36:39]
	v_mfma_f32_16x16x32_bf16 v[32:35], v[204:207], v[172:175], v[32:35]
	v_mfma_f32_16x16x32_bf16 v[20:23], v[196:199], v[180:183], v[20:23]
	v_mfma_f32_16x16x32_bf16 v[16:19], v[204:207], v[180:183], v[16:19]
	v_mfma_f32_16x16x32_bf16 v[4:7], v[196:199], v[188:191], v[4:7]
	v_mfma_f32_16x16x32_bf16 v[0:3], v[204:207], v[188:191], v[0:3]
	s_add_i32 s6, s6, 2
	s_addk_i32 s56, 0x100
	s_addk_i32 s7, 0x100
	s_cmp_gt_u32 s6, 29
	s_barrier
	s_cbranch_scc0 .LBB0_282
	v_mov_b32_e32 v135, v148
	v_mov_b32_e32 v134, v149
	s_lshl_b32 s0, s64, 8
	s_or_b32 s0, s0, s38
	v_lshl_add_u32 v134, v134, 3, s0
	s_lshl_b32 s0, s8, 8
	s_add_i32 s0, s0, s37
	v_add_u32_e32 v136, s0, v135
	s_and_b32 s0, s64, -4
	s_cmp_eq_u32 s0, 8
	s_cselect_b64 s[66:67], -1, 0
	s_cmp_gt_u32 s64, 9
	s_cselect_b64 s[6:7], -1, 0
	s_and_b64 s[6:7], s[6:7], exec
	s_movk_i32 s1, 0xf600
	v_mov_b64_e32 v[138:139], s[26:27]
	s_cselect_b32 s7, s1, 0xfffff800
	s_mov_b32 s1, 0x3040000
	v_ashrrev_i32_e32 v137, 31, v136
	v_mad_i64_i32 v[138:139], s[8:9], v136, s92, v[138:139]
	v_ashrrev_i32_e32 v135, 31, v134
	s_cselect_b32 s6, s1, 0x2040000
	s_cmp_lg_u32 s0, 8
	v_lshlrev_b64 v[140:141], 11, v[136:137]
	v_lshl_add_u64 v[142:143], v[134:135], 1, v[138:139]
	v_add_u32_e32 v138, s7, v134
	v_cvt_pk_bf16_f32 v152, v124, v125
	v_cvt_pk_bf16_f32 v153, v126, v127
	v_cvt_pk_bf16_f32 v154, v120, v121
	v_cvt_pk_bf16_f32 v155, v122, v123
	global_store_dwordx4 v[142:143], v[152:155], off
	s_cbranch_scc1 .LBB0_285
	s_lshl_b32 s0, s6, 2
	s_add_u32 s8, s83, s0
	s_addc_u32 s9, s86, 0
	v_lshl_add_u64 v[152:153], s[8:9], 0, v[140:141]
	v_ashrrev_i32_e32 v139, 31, v138
	v_lshl_add_u64 v[152:153], v[138:139], 2, v[152:153]
	global_store_dwordx4 v[152:153], v[124:127], off
	global_store_dwordx4 v[152:153], v[120:123], off offset:16
